# p4team + P7 unit boundaries: As[1][1] of the next unit staged before the epilogue stores, peeled first iteration with store-tolerant waits
# baseline (speedup 1.0000x reference)
; __device__ __forceinline__ unsigned long long rt() { return __builtin_amdgcn_s_memrealtime(); }
; __device__ __forceinline__ unsigned xb_ld(unsigned* p)              { return __hip_atomic_load(p, __ATOMIC_RELAXED, __HIP_MEMORY_SCOPE_AGENT); }
; #define XB_SPIN(cond, bar) do { unsigned _sp = 0; while (cond) { __builtin_amdgcn_s_sleep(1); \
;     if ((++_sp & 255u) == 0u) { if (xb_ld(&(bar)[XB_TMO])) break; if (_sp > XB_SPIN_CAP) { atomicAdd(&(bar)[XB_TMO], 1u); break; } } } } while (0)
; __global__ void __launch_bounds__(NWAVES * 64, 2) fwd(Args args) {
;     ...
;     if (IN(7)) {
;         const unsigned long long amp_t0_7 = (PROBE_AMP == 7) ? rt() : 0ull;
;         if (MISC[10] != 0u && team_pm >= 32) { if (tid == 0) { const int q_ = 2 * (team_pm - 32);
;                 XB_SPIN(xb_ld((unsigned*)(ctl + CW_TEAM) + 32 * q_) < 4u, bar.bar); XB_SPIN(xb_ld((unsigned*)(ctl + CW_TEAM) + 32 * (q_ + 1)) < 4u, bar.bar); }
;             __syncthreads(); }
.LBB0_1201:
.LBB0_1202:
	s_mov_b32 s98, 0
	s_cmp_lt_i32 s56, 8
	s_cselect_b64 s[0:1], -1, 0
	s_cmp_gt_i32 s57, 7
	s_cselect_b64 s[6:7], -1, 0
	s_and_b64 s[0:1], s[0:1], s[6:7]
	s_andn2_b64 vcc, exec, s[0:1]
	s_cbranch_vccnz .LBB0_1322
	s_add_i32 s0, 0, 0x22968
	s_waitcnt vmcnt(0)
	v_mov_b32_e32 v1, s0
	ds_read_b32 v1, v1
	s_cmp_gt_u32 s4, 31
	s_cselect_b64 s[0:1], -1, 0
	s_waitcnt lgkmcnt(0)
	v_cmp_ne_u32_e32 vcc, 0, v1
	s_and_b64 s[0:1], vcc, s[0:1]
	s_andn2_b64 vcc, exec, s[0:1]
	s_cbranch_vccnz .LBB0_1231
	s_and_saveexec_b64 s[0:1], s[96:97]
	s_cbranch_execz .LBB0_1230
	s_lshl_b32 s4, s3, 8
	s_add_u32 s6, s60, s4
	s_addc_u32 s7, s61, 0
	v_mov_b32_e32 v1, 0x1e000
	global_load_dword v1, v1, s[6:7] sc1
	s_add_u32 s4, s6, 0x20000
	s_addc_u32 s5, s7, 0
	s_add_u32 s6, s6, 0x1e000
	s_addc_u32 s7, s7, 0
	s_waitcnt vmcnt(0)
	v_cmp_lt_u32_e32 vcc, 3, v1
	s_cbranch_vccnz .LBB0_1218
	s_mov_b32 s18, 1
	v_mov_b32_e32 v1, 0
	s_branch .LBB0_1208

;     __host__ __device__ bool next(int i, Unit& u) const { if (!so.next(i >> 1, u)) return false; u.k0 = (i & 1) * 512; return true; }
;     __host__ __device__ bool next(int i, Unit& u) const { if (!so.next(i, u)) return false; u.pe = main_tile(u.pn); return true; }
;     __host__ __device__ bool next(int i, Unit& u) const { if (start + i * stride >= limit) return false; if (!so.next(i, u)) return false; u.pe = late_tile(u.pn); return true; }
; #define PG8_STAGE(bufoff, gbase, voff) do { _Pragma("unroll") for (int _i = 0; _i < 2; ++_i) \
;         __builtin_amdgcn_global_load_lds((const unsigned*)((const char*)(gbase) + (voff)[_i]), (PG8_LAS unsigned*)(lds + (bufoff) + ldsw + _i * 8192), 16, 0, 0); } while (0)
; #define PG8_WAIT_V(n) asm volatile("s_waitcnt vmcnt(" #n ")" ::: "memory")
; #define PG8_WAIT_L(n) asm volatile("s_waitcnt lgkmcnt(" #n ")" ::: "memory")
; template <class Epi, class Sched, bool ALIGN_EPI = false, bool SP2 = false>
; __device__ __forceinline__ void gemm_phase(PG8_LAS unsigned char* lds, const Gemm g, const Sched& S, const Epi& E) {
;     ...
;         const bool has_next = S.next(ui + 1, nxt);
;         const char* nA = has_next ? (const char*)g.A + (size_t)nxt.pm * tstepA + (size_t)nxt.k0 * 2 : cA; const char* nB = has_next ? (const char*)g.Bt + (size_t)nxt.pn * tstepB + (size_t)nxt.k0 * 2 : cB;
;         for (int t = 0; t < nt; t += 2) {
;             const bool last = (t == nt - 2);
;             const char* a1 = cA + (size_t)(t + 1) * kstepA;
;             const char* a2 = last ? nA : cA + (size_t)(t + 2) * kstepA; const char* b2 = last ? nB : cB + (size_t)(t + 2) * kstep;
;             const char* a3 = a2 + kstepA; const char* b3 = b2 + kstep;
;             if (last && has_next) S.a_ready(nxt);
;             if constexpr (SP2) {
;             PG8_LDB(B0, 0, 0); PG8_LDB(B1, 0, 1); PG8_SCHED; PG8_LDA(At, 0, 0); PG8_STAGE(PG8_SA(1, 1), a1 + hstepA, voffA);
;             PG8_WAIT_V(8); PG8_WAIT_L(0); PG8_BAR; PG8_MMA(0, 0, At, B0); PG8_MMA(0, 1, At, B1); PG8_BAR; PG8_SCHED;
;     ...
;         if (!keep_) {
; #pragma unroll
;         for (int a = 0; a < 2; ++a)
; #pragma unroll
;             for (int b = 0; b < 2; ++b)
; #pragma unroll
;                 for (int m = 0; m < 4; ++m)
; #pragma unroll
;                     for (int n = 0; n < 2; ++n) acc[a][b][m][n] = (f32x4){0.f, 0.f, 0.f, 0.f};
;         }
;         cur = nxt; cA = nA; cB = nB; ++ui;
.LBB0_1243:
	s_ashr_i32 s19, s18, 31
	s_lshl_b64 s[22:23], s[18:19], 19
	s_add_u32 s22, s20, s22
	s_addc_u32 s23, s21, s23
	s_and_b64 s[24:25], s[0:1], exec
	s_cselect_b32 s19, s23, s31
	s_cselect_b32 s51, s22, s30
	s_ashr_i32 s17, s16, 31
	s_lshl_b64 s[24:25], s[16:17], 19
	s_add_u32 s24, s14, s24
	s_addc_u32 s25, s15, s25
	s_and_b64 s[38:39], s[0:1], exec
	s_cselect_b32 s17, s25, s37
	s_cselect_b32 s62, s24, s36
	s_add_u32 s30, s30, 0x40080
	s_addc_u32 s31, s31, 0
	s_add_u32 s63, s36, 0x100
	v_mov_b32_e32 v2, 0
	s_addc_u32 s64, s37, 0
	s_mov_b32 s65, -2
	v_mov_b32_e32 v3, v2
	v_mov_b32_e32 v4, v2
	v_mov_b32_e32 v5, v2
	v_mov_b32_e32 v6, v2
	v_mov_b32_e32 v7, v2
	v_mov_b32_e32 v8, v2
	v_mov_b32_e32 v9, v2
	v_mov_b32_e32 v18, v2
	v_mov_b32_e32 v19, v2
	v_mov_b32_e32 v20, v2
	v_mov_b32_e32 v21, v2
	v_mov_b32_e32 v22, v2
	v_mov_b32_e32 v23, v2
	v_mov_b32_e32 v24, v2
	v_mov_b32_e32 v25, v2
	v_mov_b32_e32 v34, v2
	v_mov_b32_e32 v35, v2
	v_mov_b32_e32 v36, v2
	v_mov_b32_e32 v37, v2
	v_mov_b32_e32 v38, v2
	v_mov_b32_e32 v39, v2
	v_mov_b32_e32 v40, v2
	v_mov_b32_e32 v41, v2
	v_mov_b32_e32 v50, v2
	v_mov_b32_e32 v51, v2
	v_mov_b32_e32 v52, v2
	v_mov_b32_e32 v53, v2
	v_mov_b32_e32 v54, v2
	v_mov_b32_e32 v55, v2
	v_mov_b32_e32 v56, v2
	v_mov_b32_e32 v57, v2
	v_mov_b32_e32 v10, v2
	v_mov_b32_e32 v11, v2
	v_mov_b32_e32 v12, v2
	v_mov_b32_e32 v13, v2
	v_mov_b32_e32 v14, v2
	v_mov_b32_e32 v15, v2
	v_mov_b32_e32 v16, v2
	v_mov_b32_e32 v17, v2
	v_mov_b32_e32 v26, v2
	v_mov_b32_e32 v27, v2
	v_mov_b32_e32 v28, v2
	v_mov_b32_e32 v29, v2
	v_mov_b32_e32 v30, v2
	v_mov_b32_e32 v31, v2
	v_mov_b32_e32 v32, v2
	v_mov_b32_e32 v33, v2
	v_mov_b32_e32 v42, v2
	v_mov_b32_e32 v43, v2
	v_mov_b32_e32 v44, v2
	v_mov_b32_e32 v45, v2
	v_mov_b32_e32 v46, v2
	v_mov_b32_e32 v47, v2
	v_mov_b32_e32 v48, v2
	v_mov_b32_e32 v49, v2
	v_mov_b32_e32 v58, v2
	v_mov_b32_e32 v59, v2
	v_mov_b32_e32 v60, v2
	v_mov_b32_e32 v61, v2
	v_mov_b32_e32 v62, v2
	v_mov_b32_e32 v63, v2
	v_mov_b32_e32 v64, v2
	v_mov_b32_e32 v65, v2
	v_mov_b32_e32 v66, v2
	v_mov_b32_e32 v67, v2
	v_mov_b32_e32 v68, v2
	v_mov_b32_e32 v69, v2
	v_mov_b32_e32 v70, v2
	v_mov_b32_e32 v71, v2
	v_mov_b32_e32 v72, v2
	v_mov_b32_e32 v73, v2
	v_mov_b32_e32 v82, v2
	v_mov_b32_e32 v83, v2
	v_mov_b32_e32 v84, v2
	v_mov_b32_e32 v85, v2
	v_mov_b32_e32 v86, v2
	v_mov_b32_e32 v87, v2
	v_mov_b32_e32 v88, v2
	v_mov_b32_e32 v89, v2
	v_mov_b32_e32 v98, v2
	v_mov_b32_e32 v99, v2
	v_mov_b32_e32 v100, v2
	v_mov_b32_e32 v101, v2
	v_mov_b32_e32 v102, v2
	v_mov_b32_e32 v103, v2
	v_mov_b32_e32 v104, v2
	v_mov_b32_e32 v105, v2
	v_mov_b32_e32 v114, v2
	v_mov_b32_e32 v115, v2
	v_mov_b32_e32 v116, v2
	v_mov_b32_e32 v117, v2
	v_mov_b32_e32 v118, v2
	v_mov_b32_e32 v119, v2
	v_mov_b32_e32 v120, v2
	v_mov_b32_e32 v121, v2
	v_mov_b32_e32 v74, v2
	v_mov_b32_e32 v75, v2
	v_mov_b32_e32 v76, v2
	v_mov_b32_e32 v77, v2
	v_mov_b32_e32 v78, v2
	v_mov_b32_e32 v79, v2
	v_mov_b32_e32 v80, v2
	v_mov_b32_e32 v81, v2
	v_mov_b32_e32 v90, v2
	v_mov_b32_e32 v91, v2
	v_mov_b32_e32 v92, v2
	v_mov_b32_e32 v93, v2
	v_mov_b32_e32 v94, v2
	v_mov_b32_e32 v95, v2
	v_mov_b32_e32 v96, v2
	v_mov_b32_e32 v97, v2
	v_mov_b32_e32 v106, v2
	v_mov_b32_e32 v107, v2
	v_mov_b32_e32 v108, v2
	v_mov_b32_e32 v109, v2
	v_mov_b32_e32 v110, v2
	v_mov_b32_e32 v111, v2
	v_mov_b32_e32 v112, v2
	v_mov_b32_e32 v113, v2
	v_mov_b32_e32 v122, v2
	v_mov_b32_e32 v123, v2
	v_mov_b32_e32 v124, v2
	v_mov_b32_e32 v125, v2
	v_mov_b32_e32 v126, v2
	v_mov_b32_e32 v127, v2
	v_mov_b32_e32 v128, v2
	v_mov_b32_e32 v129, v2
	s_cmp_lg_u32 s98, 0
	s_cbranch_scc1 .Lub_p7_first
.LBB0_1244:
	ds_read_b128 v[158:161], v154
	ds_read_b128 v[162:165], v154 offset:1024
	ds_read_b128 v[166:169], v154 offset:2048
	ds_read_b128 v[170:173], v154 offset:3072
	ds_read_b128 v[174:177], v155
	ds_read_b128 v[178:181], v155 offset:1024
	ds_read_b128 v[182:185], v155 offset:2048
	ds_read_b128 v[186:189], v155 offset:3072
	s_add_u32 s36, s30, 0xfffc0080
	s_addc_u32 s37, s31, -1
	s_cmp_eq_u32 s65, 12
	s_cselect_b32 s39, s19, s37
	s_cselect_b32 s38, s51, s36
	s_cselect_b32 s37, s17, s64
	s_cselect_b32 s36, s62, s63
	v_lshl_add_u64 v[222:223], s[30:31], 0, v[146:147]
	s_add_i32 m0, s33, 0xc000
	ds_read_b128 v[190:193], v156
	ds_read_b128 v[194:197], v156 offset:1024
	ds_read_b128 v[198:201], v156 offset:2048
	ds_read_b128 v[202:205], v156 offset:3072
	ds_read_b128 v[206:209], v156 offset:4096
	ds_read_b128 v[210:213], v156 offset:5120
	ds_read_b128 v[214:217], v156 offset:6144
	ds_read_b128 v[218:221], v156 offset:7168
	global_load_lds_dwordx4 v[222:223], off
	v_lshl_add_u64 v[222:223], s[30:31], 0, v[148:149]
	s_add_i32 m0, s33, 0xe000
	s_nop 0
	global_load_lds_dwordx4 v[222:223], off
	s_waitcnt vmcnt(8)
	s_waitcnt lgkmcnt(0)
	s_setprio 1
	s_barrier
; #define PG8_STAGE(bufoff, gbase, voff) do { _Pragma("unroll") for (int _i = 0; _i < 2; ++_i) \
;         __builtin_amdgcn_global_load_lds((const unsigned*)((const char*)(gbase) + (voff)[_i]), (PG8_LAS unsigned*)(lds + (bufoff) + ldsw + _i * 8192), 16, 0, 0); } while (0)
; #define PG8_LDA(dst, b, h) do { _Pragma("unroll") for (int m = 0; m < 4; ++m) _Pragma("unroll") for (int k = 0; k < 2; ++k) dst[m][k] = *(const PG8_LAS bf16x8*)(lds + PG8_SA(b, h) + aoff + m * 2048 + k * 1024); } while (0)
; #define PG8_MMA(ai, bj, At, Bt) do { __builtin_amdgcn_s_setprio(1); _Pragma("unroll") for (int m = 0; m < 4; ++m) _Pragma("unroll") for (int n = 0; n < 2; ++n) _Pragma("unroll") for (int k = 0; k < 2; ++k) \
;         acc[ai][bj][m][n] = __builtin_amdgcn_mfma_f32_16x16x32_bf16(Bt[n][k], At[m][k], acc[ai][bj][m][n], 0, 0, 0); __builtin_amdgcn_s_setprio(0); } while (0)
; #define PG8_WAIT_V(n) asm volatile("s_waitcnt vmcnt(" #n ")" ::: "memory")
; #define PG8_WAIT_L(n) asm volatile("s_waitcnt lgkmcnt(" #n ")" ::: "memory")
; #define PG8_BAR __builtin_amdgcn_s_barrier()
; #define PG8_SCHED __builtin_amdgcn_sched_barrier(0)
; template <class Epi, class Sched, bool ALIGN_EPI = false, bool SP2 = false>
; __device__ __forceinline__ void gemm_phase(PG8_LAS unsigned char* lds, const Gemm g, const Sched& S, const Epi& E) {
;     ...
;             PG8_WAIT_V(8); PG8_WAIT_L(0); PG8_BAR; PG8_MMA(0, 0, At, B0); PG8_MMA(0, 1, At, B1); PG8_BAR; PG8_SCHED;
;             PG8_LDA(At, 0, 1); PG8_STAGE(PG8_SB(0, 0), b2, voffB); PG8_STAGE(PG8_SB(0, 1), b2 + hstepB, voffB); PG8_STAGE(PG8_SA(0, 0), a2, voffA);
;             PG8_WAIT_V(8); PG8_WAIT_L(0); PG8_BAR; PG8_MMA(1, 0, At, B0); PG8_MMA(1, 1, At, B1); PG8_BAR; PG8_SCHED;
	v_mfma_f32_16x16x32_bf16 v[126:129], v[158:161], v[190:193], v[126:129]
	v_mfma_f32_16x16x32_bf16 v[122:125], v[166:169], v[190:193], v[122:125]
	v_mfma_f32_16x16x32_bf16 v[110:113], v[158:161], v[198:201], v[110:113]
	v_mfma_f32_16x16x32_bf16 v[106:109], v[166:169], v[198:201], v[106:109]
	v_mfma_f32_16x16x32_bf16 v[94:97], v[158:161], v[206:209], v[94:97]
	v_mfma_f32_16x16x32_bf16 v[90:93], v[166:169], v[206:209], v[90:93]
	v_mfma_f32_16x16x32_bf16 v[78:81], v[158:161], v[214:217], v[78:81]
	v_mfma_f32_16x16x32_bf16 v[74:77], v[166:169], v[214:217], v[74:77]
	v_mfma_f32_16x16x32_bf16 v[126:129], v[162:165], v[194:197], v[126:129]
	v_mfma_f32_16x16x32_bf16 v[122:125], v[170:173], v[194:197], v[122:125]
	v_mfma_f32_16x16x32_bf16 v[110:113], v[162:165], v[202:205], v[110:113]
	v_mfma_f32_16x16x32_bf16 v[106:109], v[170:173], v[202:205], v[106:109]
	v_mfma_f32_16x16x32_bf16 v[94:97], v[162:165], v[210:213], v[94:97]
	v_mfma_f32_16x16x32_bf16 v[90:93], v[170:173], v[210:213], v[90:93]
	v_mfma_f32_16x16x32_bf16 v[78:81], v[162:165], v[218:221], v[78:81]
	v_mfma_f32_16x16x32_bf16 v[74:77], v[170:173], v[218:221], v[74:77]
	v_mfma_f32_16x16x32_bf16 v[118:121], v[174:177], v[190:193], v[118:121]
	v_mfma_f32_16x16x32_bf16 v[114:117], v[182:185], v[190:193], v[114:117]
	v_mfma_f32_16x16x32_bf16 v[102:105], v[174:177], v[198:201], v[102:105]
	v_mfma_f32_16x16x32_bf16 v[98:101], v[182:185], v[198:201], v[98:101]
	v_mfma_f32_16x16x32_bf16 v[86:89], v[174:177], v[206:209], v[86:89]
	v_mfma_f32_16x16x32_bf16 v[82:85], v[182:185], v[206:209], v[82:85]
	v_mfma_f32_16x16x32_bf16 v[70:73], v[174:177], v[214:217], v[70:73]
	v_mfma_f32_16x16x32_bf16 v[66:69], v[182:185], v[214:217], v[66:69]
	v_mfma_f32_16x16x32_bf16 v[118:121], v[178:181], v[194:197], v[118:121]
	v_mfma_f32_16x16x32_bf16 v[114:117], v[186:189], v[194:197], v[114:117]
	v_mfma_f32_16x16x32_bf16 v[102:105], v[178:181], v[202:205], v[102:105]
	v_mfma_f32_16x16x32_bf16 v[98:101], v[186:189], v[202:205], v[98:101]
	v_mfma_f32_16x16x32_bf16 v[86:89], v[178:181], v[210:213], v[86:89]
	v_mfma_f32_16x16x32_bf16 v[82:85], v[186:189], v[210:213], v[82:85]
	v_mfma_f32_16x16x32_bf16 v[70:73], v[178:181], v[218:221], v[70:73]
	v_mfma_f32_16x16x32_bf16 v[66:69], v[186:189], v[218:221], v[66:69]
	s_barrier
	s_setprio 0
	s_add_i32 s66, s48, s4
	v_lshl_add_u64 v[222:223], s[36:37], 0, v[132:133]
	s_mov_b32 m0, s66
	ds_read_b128 v[190:193], v156 offset:16384
	ds_read_b128 v[194:197], v156 offset:17408
	ds_read_b128 v[198:201], v156 offset:18432
	ds_read_b128 v[202:205], v156 offset:19456
	ds_read_b128 v[206:209], v156 offset:20480
	ds_read_b128 v[210:213], v156 offset:21504
	ds_read_b128 v[214:217], v156 offset:22528
	ds_read_b128 v[218:221], v156 offset:23552
	global_load_lds_dwordx4 v[222:223], off
	s_add_i32 m0, s66, 0x2000
	s_add_u32 s66, s36, 0x40000
	v_lshl_add_u64 v[224:225], s[36:37], 0, v[136:137]
	s_addc_u32 s67, s37, 0
	s_add_i32 s68, s49, s4
	global_load_lds_dwordx4 v[224:225], off
	v_lshl_add_u64 v[226:227], s[66:67], 0, v[132:133]
	s_mov_b32 m0, s68
	v_lshl_add_u64 v[228:229], s[38:39], 0, v[134:135]
	global_load_lds_dwordx4 v[226:227], off
	v_lshl_add_u64 v[226:227], s[66:67], 0, v[136:137]
	s_add_i32 m0, s68, 0x2000
	s_nop 0
	global_load_lds_dwordx4 v[226:227], off
	v_lshl_add_u64 v[226:227], s[38:39], 0, v[130:131]
	s_mov_b32 m0, s33
	s_nop 0
	global_load_lds_dwordx4 v[226:227], off
	s_mov_b32 m0, s35
	s_nop 0
	global_load_lds_dwordx4 v[228:229], off
	s_waitcnt vmcnt(8)
	s_waitcnt lgkmcnt(0)
	s_setprio 1
	s_barrier
	v_mfma_f32_16x16x32_bf16 v[62:65], v[158:161], v[190:193], v[62:65]
	v_mfma_f32_16x16x32_bf16 v[58:61], v[166:169], v[190:193], v[58:61]
	v_mfma_f32_16x16x32_bf16 v[46:49], v[158:161], v[198:201], v[46:49]
	v_mfma_f32_16x16x32_bf16 v[42:45], v[166:169], v[198:201], v[42:45]
	v_mfma_f32_16x16x32_bf16 v[30:33], v[158:161], v[206:209], v[30:33]
	v_mfma_f32_16x16x32_bf16 v[26:29], v[166:169], v[206:209], v[26:29]
	v_mfma_f32_16x16x32_bf16 v[14:17], v[158:161], v[214:217], v[14:17]
	v_mfma_f32_16x16x32_bf16 v[10:13], v[166:169], v[214:217], v[10:13]
	v_mfma_f32_16x16x32_bf16 v[62:65], v[162:165], v[194:197], v[62:65]
	v_mfma_f32_16x16x32_bf16 v[58:61], v[170:173], v[194:197], v[58:61]
	v_mfma_f32_16x16x32_bf16 v[46:49], v[162:165], v[202:205], v[46:49]
	v_mfma_f32_16x16x32_bf16 v[42:45], v[170:173], v[202:205], v[42:45]
	v_mfma_f32_16x16x32_bf16 v[30:33], v[162:165], v[210:213], v[30:33]
	v_mfma_f32_16x16x32_bf16 v[26:29], v[170:173], v[210:213], v[26:29]
	v_mfma_f32_16x16x32_bf16 v[14:17], v[162:165], v[218:221], v[14:17]
	v_mfma_f32_16x16x32_bf16 v[10:13], v[170:173], v[218:221], v[10:13]
	v_mfma_f32_16x16x32_bf16 v[54:57], v[174:177], v[190:193], v[54:57]
	v_mfma_f32_16x16x32_bf16 v[50:53], v[182:185], v[190:193], v[50:53]
	v_mfma_f32_16x16x32_bf16 v[38:41], v[174:177], v[198:201], v[38:41]
	v_mfma_f32_16x16x32_bf16 v[34:37], v[182:185], v[198:201], v[34:37]
	v_mfma_f32_16x16x32_bf16 v[22:25], v[174:177], v[206:209], v[22:25]
	v_mfma_f32_16x16x32_bf16 v[18:21], v[182:185], v[206:209], v[18:21]
	v_mfma_f32_16x16x32_bf16 v[6:9], v[174:177], v[214:217], v[6:9]
	v_mfma_f32_16x16x32_bf16 v[2:5], v[182:185], v[214:217], v[2:5]
	v_mfma_f32_16x16x32_bf16 v[54:57], v[178:181], v[194:197], v[54:57]
	v_mfma_f32_16x16x32_bf16 v[50:53], v[186:189], v[194:197], v[50:53]
	v_mfma_f32_16x16x32_bf16 v[38:41], v[178:181], v[202:205], v[38:41]
	v_mfma_f32_16x16x32_bf16 v[34:37], v[186:189], v[202:205], v[34:37]
	v_mfma_f32_16x16x32_bf16 v[22:25], v[178:181], v[210:213], v[22:25]
	v_mfma_f32_16x16x32_bf16 v[18:21], v[186:189], v[210:213], v[18:21]
	v_mfma_f32_16x16x32_bf16 v[6:9], v[178:181], v[218:221], v[6:9]
	v_mfma_f32_16x16x32_bf16 v[2:5], v[186:189], v[218:221], v[2:5]
	s_barrier
; #define PG8_STAGE(bufoff, gbase, voff) do { _Pragma("unroll") for (int _i = 0; _i < 2; ++_i) \
;         __builtin_amdgcn_global_load_lds((const unsigned*)((const char*)(gbase) + (voff)[_i]), (PG8_LAS unsigned*)(lds + (bufoff) + ldsw + _i * 8192), 16, 0, 0); } while (0)
; #define PG8_LDA(dst, b, h) do { _Pragma("unroll") for (int m = 0; m < 4; ++m) _Pragma("unroll") for (int k = 0; k < 2; ++k) dst[m][k] = *(const PG8_LAS bf16x8*)(lds + PG8_SA(b, h) + aoff + m * 2048 + k * 1024); } while (0)
; #define PG8_LDB(dst, b, h) do { _Pragma("unroll") for (int n = 0; n < 2; ++n) _Pragma("unroll") for (int k = 0; k < 2; ++k) dst[n][k] = *(const PG8_LAS bf16x8*)(lds + PG8_SB(b, h) + boff + n * 2048 + k * 1024); } while (0)
; #define PG8_MMA(ai, bj, At, Bt) do { __builtin_amdgcn_s_setprio(1); _Pragma("unroll") for (int m = 0; m < 4; ++m) _Pragma("unroll") for (int n = 0; n < 2; ++n) _Pragma("unroll") for (int k = 0; k < 2; ++k) \
;         acc[ai][bj][m][n] = __builtin_amdgcn_mfma_f32_16x16x32_bf16(Bt[n][k], At[m][k], acc[ai][bj][m][n], 0, 0, 0); __builtin_amdgcn_s_setprio(0); } while (0)
; #define PG8_WAIT_V(n) asm volatile("s_waitcnt vmcnt(" #n ")" ::: "memory")
; #define PG8_WAIT_L(n) asm volatile("s_waitcnt lgkmcnt(" #n ")" ::: "memory")
; #define PG8_BAR __builtin_amdgcn_s_barrier()
; #define PG8_SCHED __builtin_amdgcn_sched_barrier(0)
; template <class Epi, class Sched, bool ALIGN_EPI = false, bool SP2 = false>
; __device__ __forceinline__ void gemm_phase(PG8_LAS unsigned char* lds, const Gemm g, const Sched& S, const Epi& E) {
;     ...
;             PG8_LDB(B0, 1, 0); PG8_LDB(B1, 1, 1); PG8_SCHED; PG8_LDA(At, 1, 0); PG8_STAGE(PG8_SA(0, 1), a2 + hstepA, voffA);
;             PG8_WAIT_V(8); PG8_WAIT_L(0); PG8_BAR; PG8_MMA(0, 0, At, B0); PG8_MMA(0, 1, At, B1); PG8_BAR; PG8_SCHED;
;             PG8_LDA(At, 1, 1); PG8_STAGE(PG8_SB(1, 0), b3, voffB); PG8_STAGE(PG8_SB(1, 1), b3 + hstepB, voffB); PG8_STAGE(PG8_SA(1, 0), a3, voffA);
;             PG8_WAIT_V(8); PG8_WAIT_L(0); PG8_BAR; PG8_MMA(1, 0, At, B0); PG8_MMA(1, 1, At, B1); PG8_BAR; PG8_SCHED;
	s_setprio 0
	s_add_i32 s66, 0, 0x18000
	v_add_u32_e32 v157, s66, v1
	s_add_i32 s67, 0, 0x1c000
	ds_read_b128 v[158:161], v157
	ds_read_b128 v[162:165], v157 offset:1024
	ds_read_b128 v[166:169], v157 offset:2048
	ds_read_b128 v[170:173], v157 offset:3072
	v_add_u32_e32 v157, s67, v1
	ds_read_b128 v[174:177], v157
	ds_read_b128 v[178:181], v157 offset:1024
	ds_read_b128 v[182:185], v157 offset:2048
	ds_read_b128 v[186:189], v157 offset:3072
	s_add_u32 s38, s38, 0x40000
	s_addc_u32 s39, s39, 0
	s_mov_b32 m0, s40
	v_lshl_add_u64 v[230:231], s[38:39], 0, v[130:131]
	ds_read_b128 v[190:193], v156 offset:32768
	ds_read_b128 v[194:197], v156 offset:33792
	ds_read_b128 v[198:201], v156 offset:34816
	ds_read_b128 v[202:205], v156 offset:35840
	ds_read_b128 v[206:209], v156 offset:36864
	ds_read_b128 v[210:213], v156 offset:37888
	ds_read_b128 v[214:217], v156 offset:38912
	ds_read_b128 v[218:221], v156 offset:39936
	global_load_lds_dwordx4 v[230:231], off
	v_lshl_add_u64 v[230:231], s[38:39], 0, v[134:135]
	s_mov_b32 m0, s41
	s_nop 0
	global_load_lds_dwordx4 v[230:231], off
	s_waitcnt vmcnt(8)
	s_waitcnt lgkmcnt(0)
	s_setprio 1
	s_barrier
	v_mfma_f32_16x16x32_bf16 v[126:129], v[158:161], v[190:193], v[126:129]
	v_mfma_f32_16x16x32_bf16 v[122:125], v[166:169], v[190:193], v[122:125]
	v_mfma_f32_16x16x32_bf16 v[110:113], v[158:161], v[198:201], v[110:113]
	v_mfma_f32_16x16x32_bf16 v[106:109], v[166:169], v[198:201], v[106:109]
	v_mfma_f32_16x16x32_bf16 v[94:97], v[158:161], v[206:209], v[94:97]
	v_mfma_f32_16x16x32_bf16 v[90:93], v[166:169], v[206:209], v[90:93]
	v_mfma_f32_16x16x32_bf16 v[78:81], v[158:161], v[214:217], v[78:81]
	v_mfma_f32_16x16x32_bf16 v[74:77], v[166:169], v[214:217], v[74:77]
	v_mfma_f32_16x16x32_bf16 v[126:129], v[162:165], v[194:197], v[126:129]
	v_mfma_f32_16x16x32_bf16 v[122:125], v[170:173], v[194:197], v[122:125]
	v_mfma_f32_16x16x32_bf16 v[110:113], v[162:165], v[202:205], v[110:113]
	v_mfma_f32_16x16x32_bf16 v[106:109], v[170:173], v[202:205], v[106:109]
	v_mfma_f32_16x16x32_bf16 v[94:97], v[162:165], v[210:213], v[94:97]
	v_mfma_f32_16x16x32_bf16 v[90:93], v[170:173], v[210:213], v[90:93]
	v_mfma_f32_16x16x32_bf16 v[78:81], v[162:165], v[218:221], v[78:81]
	v_mfma_f32_16x16x32_bf16 v[74:77], v[170:173], v[218:221], v[74:77]
	v_mfma_f32_16x16x32_bf16 v[118:121], v[174:177], v[190:193], v[118:121]
	v_mfma_f32_16x16x32_bf16 v[114:117], v[182:185], v[190:193], v[114:117]
	v_mfma_f32_16x16x32_bf16 v[102:105], v[174:177], v[198:201], v[102:105]
	v_mfma_f32_16x16x32_bf16 v[98:101], v[182:185], v[198:201], v[98:101]
	v_mfma_f32_16x16x32_bf16 v[86:89], v[174:177], v[206:209], v[86:89]
	v_mfma_f32_16x16x32_bf16 v[82:85], v[182:185], v[206:209], v[82:85]
	v_mfma_f32_16x16x32_bf16 v[70:73], v[174:177], v[214:217], v[70:73]
	v_mfma_f32_16x16x32_bf16 v[66:69], v[182:185], v[214:217], v[66:69]
	v_mfma_f32_16x16x32_bf16 v[118:121], v[178:181], v[194:197], v[118:121]
	v_mfma_f32_16x16x32_bf16 v[114:117], v[186:189], v[194:197], v[114:117]
	v_mfma_f32_16x16x32_bf16 v[102:105], v[178:181], v[202:205], v[102:105]
	v_mfma_f32_16x16x32_bf16 v[98:101], v[186:189], v[202:205], v[98:101]
	v_mfma_f32_16x16x32_bf16 v[86:89], v[178:181], v[210:213], v[86:89]
	v_mfma_f32_16x16x32_bf16 v[82:85], v[186:189], v[210:213], v[82:85]
	v_mfma_f32_16x16x32_bf16 v[70:73], v[178:181], v[218:221], v[70:73]
	v_mfma_f32_16x16x32_bf16 v[66:69], v[186:189], v[218:221], v[66:69]
	s_barrier
	s_setprio 0
	s_add_i32 s38, s66, s4
	v_lshl_add_u64 v[222:223], v[222:223], 0, s[8:9]
	s_mov_b32 m0, s38
	ds_read_b128 v[190:193], v156 offset:49152
	ds_read_b128 v[194:197], v156 offset:50176
	ds_read_b128 v[198:201], v156 offset:51200
	ds_read_b128 v[202:205], v156 offset:52224
	ds_read_b128 v[206:209], v156 offset:53248
	ds_read_b128 v[210:213], v156 offset:54272
	ds_read_b128 v[214:217], v156 offset:55296
	ds_read_b128 v[218:221], v156 offset:56320
	global_load_lds_dwordx4 v[222:223], off
	s_add_i32 m0, s38, 0x2000
	s_add_u32 s36, s36, 0x40080
	v_lshl_add_u64 v[222:223], v[224:225], 0, s[8:9]
	s_addc_u32 s37, s37, 0
	s_add_i32 s38, s67, s4
	global_load_lds_dwordx4 v[222:223], off
	v_lshl_add_u64 v[222:223], s[36:37], 0, v[132:133]
	s_mov_b32 m0, s38
	s_nop 0
	global_load_lds_dwordx4 v[222:223], off
	v_lshl_add_u64 v[222:223], s[36:37], 0, v[136:137]
	s_add_i32 m0, s38, 0x2000
	s_nop 0
	global_load_lds_dwordx4 v[222:223], off
	v_lshl_add_u64 v[222:223], v[226:227], 0, s[8:9]
	s_mov_b32 m0, s45
	s_nop 0
	global_load_lds_dwordx4 v[222:223], off
	v_lshl_add_u64 v[222:223], v[228:229], 0, s[8:9]
	s_mov_b32 m0, s46
	s_nop 0
	global_load_lds_dwordx4 v[222:223], off
	s_waitcnt vmcnt(8)
	s_waitcnt lgkmcnt(0)
	s_setprio 1
	s_barrier
; #define PG8_STAGE(bufoff, gbase, voff) do { _Pragma("unroll") for (int _i = 0; _i < 2; ++_i) \
;         __builtin_amdgcn_global_load_lds((const unsigned*)((const char*)(gbase) + (voff)[_i]), (PG8_LAS unsigned*)(lds + (bufoff) + ldsw + _i * 8192), 16, 0, 0); } while (0)
; #define PG8_LDA(dst, b, h) do { _Pragma("unroll") for (int m = 0; m < 4; ++m) _Pragma("unroll") for (int k = 0; k < 2; ++k) dst[m][k] = *(const PG8_LAS bf16x8*)(lds + PG8_SA(b, h) + aoff + m * 2048 + k * 1024); } while (0)
; #define PG8_LDB(dst, b, h) do { _Pragma("unroll") for (int n = 0; n < 2; ++n) _Pragma("unroll") for (int k = 0; k < 2; ++k) dst[n][k] = *(const PG8_LAS bf16x8*)(lds + PG8_SB(b, h) + boff + n * 2048 + k * 1024); } while (0)
; #define PG8_MMA(ai, bj, At, Bt) do { __builtin_amdgcn_s_setprio(1); _Pragma("unroll") for (int m = 0; m < 4; ++m) _Pragma("unroll") for (int n = 0; n < 2; ++n) _Pragma("unroll") for (int k = 0; k < 2; ++k) \
;         acc[ai][bj][m][n] = __builtin_amdgcn_mfma_f32_16x16x32_bf16(Bt[n][k], At[m][k], acc[ai][bj][m][n], 0, 0, 0); __builtin_amdgcn_s_setprio(0); } while (0)
; #define PG8_WAIT_V(n) asm volatile("s_waitcnt vmcnt(" #n ")" ::: "memory")
; template <class Epi, class Sched, bool ALIGN_EPI = false, bool SP2 = false>
; __device__ __forceinline__ void gemm_phase(PG8_LAS unsigned char* lds, const Gemm g, const Sched& S, const Epi& E) {
;     ...
;             PG8_LDB(B0, 0, 0); PG8_LDB(B1, 0, 1); PG8_SCHED; PG8_LDA(At, 0, 0); PG8_STAGE(PG8_SA(1, 1), a1 + hstepA, voffA);
;             PG8_WAIT_V(8); PG8_WAIT_L(0); PG8_BAR; PG8_MMA(0, 0, At, B0); PG8_MMA(0, 1, At, B1); PG8_BAR; PG8_SCHED;
;             PG8_LDA(At, 0, 1); PG8_STAGE(PG8_SB(0, 0), b2, voffB); PG8_STAGE(PG8_SB(0, 1), b2 + hstepB, voffB); PG8_STAGE(PG8_SA(0, 0), a2, voffA);
;             PG8_WAIT_V(8); PG8_WAIT_L(0); PG8_BAR; PG8_MMA(1, 0, At, B0); PG8_MMA(1, 1, At, B1); PG8_BAR; PG8_SCHED;
;             PG8_LDB(B0, 1, 0); PG8_LDB(B1, 1, 1); PG8_SCHED; PG8_LDA(At, 1, 0); PG8_STAGE(PG8_SA(0, 1), a2 + hstepA, voffA);
;             PG8_WAIT_V(8); PG8_WAIT_L(0); PG8_BAR; PG8_MMA(0, 0, At, B0); PG8_MMA(0, 1, At, B1); PG8_BAR; PG8_SCHED;
;             PG8_LDA(At, 1, 1); PG8_STAGE(PG8_SB(1, 0), b3, voffB); PG8_STAGE(PG8_SB(1, 1), b3 + hstepB, voffB); PG8_STAGE(PG8_SA(1, 0), a3, voffA);
;             PG8_WAIT_V(8); PG8_WAIT_L(0); PG8_BAR; PG8_MMA(1, 0, At, B0); PG8_MMA(1, 1, At, B1); PG8_BAR; PG8_SCHED;
	v_mfma_f32_16x16x32_bf16 v[62:65], v[158:161], v[190:193], v[62:65]
	v_mfma_f32_16x16x32_bf16 v[58:61], v[166:169], v[190:193], v[58:61]
	v_mfma_f32_16x16x32_bf16 v[46:49], v[158:161], v[198:201], v[46:49]
	v_mfma_f32_16x16x32_bf16 v[42:45], v[166:169], v[198:201], v[42:45]
	v_mfma_f32_16x16x32_bf16 v[30:33], v[158:161], v[206:209], v[30:33]
	v_mfma_f32_16x16x32_bf16 v[26:29], v[166:169], v[206:209], v[26:29]
	v_mfma_f32_16x16x32_bf16 v[14:17], v[158:161], v[214:217], v[14:17]
	v_mfma_f32_16x16x32_bf16 v[10:13], v[166:169], v[214:217], v[10:13]
	v_mfma_f32_16x16x32_bf16 v[62:65], v[162:165], v[194:197], v[62:65]
	v_mfma_f32_16x16x32_bf16 v[58:61], v[170:173], v[194:197], v[58:61]
	v_mfma_f32_16x16x32_bf16 v[46:49], v[162:165], v[202:205], v[46:49]
	v_mfma_f32_16x16x32_bf16 v[42:45], v[170:173], v[202:205], v[42:45]
	v_mfma_f32_16x16x32_bf16 v[30:33], v[162:165], v[210:213], v[30:33]
	v_mfma_f32_16x16x32_bf16 v[26:29], v[170:173], v[210:213], v[26:29]
	v_mfma_f32_16x16x32_bf16 v[14:17], v[162:165], v[218:221], v[14:17]
	v_mfma_f32_16x16x32_bf16 v[10:13], v[170:173], v[218:221], v[10:13]
	v_mfma_f32_16x16x32_bf16 v[54:57], v[174:177], v[190:193], v[54:57]
	v_mfma_f32_16x16x32_bf16 v[50:53], v[182:185], v[190:193], v[50:53]
	v_mfma_f32_16x16x32_bf16 v[38:41], v[174:177], v[198:201], v[38:41]
	v_mfma_f32_16x16x32_bf16 v[34:37], v[182:185], v[198:201], v[34:37]
	v_mfma_f32_16x16x32_bf16 v[22:25], v[174:177], v[206:209], v[22:25]
	v_mfma_f32_16x16x32_bf16 v[18:21], v[182:185], v[206:209], v[18:21]
	v_mfma_f32_16x16x32_bf16 v[6:9], v[174:177], v[214:217], v[6:9]
	v_mfma_f32_16x16x32_bf16 v[2:5], v[182:185], v[214:217], v[2:5]
	v_mfma_f32_16x16x32_bf16 v[54:57], v[178:181], v[194:197], v[54:57]
	v_mfma_f32_16x16x32_bf16 v[50:53], v[186:189], v[194:197], v[50:53]
	v_mfma_f32_16x16x32_bf16 v[38:41], v[178:181], v[202:205], v[38:41]
	v_mfma_f32_16x16x32_bf16 v[34:37], v[186:189], v[202:205], v[34:37]
	v_mfma_f32_16x16x32_bf16 v[22:25], v[178:181], v[210:213], v[22:25]
	v_mfma_f32_16x16x32_bf16 v[18:21], v[186:189], v[210:213], v[18:21]
	v_mfma_f32_16x16x32_bf16 v[6:9], v[178:181], v[218:221], v[6:9]
	v_mfma_f32_16x16x32_bf16 v[2:5], v[186:189], v[218:221], v[2:5]
	s_barrier
	s_setprio 0
	s_add_i32 s65, s65, 2
	s_add_u32 s30, s30, 0x100
	s_addc_u32 s31, s31, 0
	s_add_u32 s63, s63, 0x100
	s_addc_u32 s64, s64, 0
	s_cmp_gt_u32 s65, 13
	s_cbranch_scc0 .LBB0_1244
	s_branch .Lub_p7_after
.Lub_p7_first:
	ds_read_b128 v[158:161], v154
	ds_read_b128 v[162:165], v154 offset:1024
	ds_read_b128 v[166:169], v154 offset:2048
	ds_read_b128 v[170:173], v154 offset:3072
	ds_read_b128 v[174:177], v155
	ds_read_b128 v[178:181], v155 offset:1024
	ds_read_b128 v[182:185], v155 offset:2048
	ds_read_b128 v[186:189], v155 offset:3072
	s_add_u32 s36, s30, 0xfffc0080
	s_addc_u32 s37, s31, -1
	s_cmp_eq_u32 s65, 12
	s_cselect_b32 s39, s19, s37
	s_cselect_b32 s38, s51, s36
	s_cselect_b32 s37, s17, s64
	s_cselect_b32 s36, s62, s63
	v_lshl_add_u64 v[222:223], s[30:31], 0, v[146:147]
	s_add_i32 m0, s33, 0xc000
	ds_read_b128 v[190:193], v156
	ds_read_b128 v[194:197], v156 offset:1024
	ds_read_b128 v[198:201], v156 offset:2048
	ds_read_b128 v[202:205], v156 offset:3072
	ds_read_b128 v[206:209], v156 offset:4096
	ds_read_b128 v[210:213], v156 offset:5120
	ds_read_b128 v[214:217], v156 offset:6144
	ds_read_b128 v[218:221], v156 offset:7168
	v_lshl_add_u64 v[222:223], s[30:31], 0, v[148:149]
	s_add_i32 m0, s33, 0xe000
	s_nop 0
	s_waitcnt vmcnt(24)
	s_waitcnt lgkmcnt(0)
	s_setprio 1
	s_barrier
	v_mfma_f32_16x16x32_bf16 v[126:129], v[158:161], v[190:193], v[126:129]
	v_mfma_f32_16x16x32_bf16 v[122:125], v[166:169], v[190:193], v[122:125]
	v_mfma_f32_16x16x32_bf16 v[110:113], v[158:161], v[198:201], v[110:113]
	v_mfma_f32_16x16x32_bf16 v[106:109], v[166:169], v[198:201], v[106:109]
	v_mfma_f32_16x16x32_bf16 v[94:97], v[158:161], v[206:209], v[94:97]
	v_mfma_f32_16x16x32_bf16 v[90:93], v[166:169], v[206:209], v[90:93]
	v_mfma_f32_16x16x32_bf16 v[78:81], v[158:161], v[214:217], v[78:81]
	v_mfma_f32_16x16x32_bf16 v[74:77], v[166:169], v[214:217], v[74:77]
	v_mfma_f32_16x16x32_bf16 v[126:129], v[162:165], v[194:197], v[126:129]
	v_mfma_f32_16x16x32_bf16 v[122:125], v[170:173], v[194:197], v[122:125]
	v_mfma_f32_16x16x32_bf16 v[110:113], v[162:165], v[202:205], v[110:113]
	v_mfma_f32_16x16x32_bf16 v[106:109], v[170:173], v[202:205], v[106:109]
	v_mfma_f32_16x16x32_bf16 v[94:97], v[162:165], v[210:213], v[94:97]
	v_mfma_f32_16x16x32_bf16 v[90:93], v[170:173], v[210:213], v[90:93]
	v_mfma_f32_16x16x32_bf16 v[78:81], v[162:165], v[218:221], v[78:81]
	v_mfma_f32_16x16x32_bf16 v[74:77], v[170:173], v[218:221], v[74:77]
	v_mfma_f32_16x16x32_bf16 v[118:121], v[174:177], v[190:193], v[118:121]
	v_mfma_f32_16x16x32_bf16 v[114:117], v[182:185], v[190:193], v[114:117]
	v_mfma_f32_16x16x32_bf16 v[102:105], v[174:177], v[198:201], v[102:105]
	v_mfma_f32_16x16x32_bf16 v[98:101], v[182:185], v[198:201], v[98:101]
	v_mfma_f32_16x16x32_bf16 v[86:89], v[174:177], v[206:209], v[86:89]
	v_mfma_f32_16x16x32_bf16 v[82:85], v[182:185], v[206:209], v[82:85]
	v_mfma_f32_16x16x32_bf16 v[70:73], v[174:177], v[214:217], v[70:73]
	v_mfma_f32_16x16x32_bf16 v[66:69], v[182:185], v[214:217], v[66:69]
	v_mfma_f32_16x16x32_bf16 v[118:121], v[178:181], v[194:197], v[118:121]
	v_mfma_f32_16x16x32_bf16 v[114:117], v[186:189], v[194:197], v[114:117]
	v_mfma_f32_16x16x32_bf16 v[102:105], v[178:181], v[202:205], v[102:105]
	v_mfma_f32_16x16x32_bf16 v[98:101], v[186:189], v[202:205], v[98:101]
	v_mfma_f32_16x16x32_bf16 v[86:89], v[178:181], v[210:213], v[86:89]
	v_mfma_f32_16x16x32_bf16 v[82:85], v[186:189], v[210:213], v[82:85]
	v_mfma_f32_16x16x32_bf16 v[70:73], v[178:181], v[218:221], v[70:73]
	v_mfma_f32_16x16x32_bf16 v[66:69], v[186:189], v[218:221], v[66:69]
	s_barrier
; #define PG8_STAGE(bufoff, gbase, voff) do { _Pragma("unroll") for (int _i = 0; _i < 2; ++_i) \
;         __builtin_amdgcn_global_load_lds((const unsigned*)((const char*)(gbase) + (voff)[_i]), (PG8_LAS unsigned*)(lds + (bufoff) + ldsw + _i * 8192), 16, 0, 0); } while (0)
; #define PG8_LDA(dst, b, h) do { _Pragma("unroll") for (int m = 0; m < 4; ++m) _Pragma("unroll") for (int k = 0; k < 2; ++k) dst[m][k] = *(const PG8_LAS bf16x8*)(lds + PG8_SA(b, h) + aoff + m * 2048 + k * 1024); } while (0)
; #define PG8_LDB(dst, b, h) do { _Pragma("unroll") for (int n = 0; n < 2; ++n) _Pragma("unroll") for (int k = 0; k < 2; ++k) dst[n][k] = *(const PG8_LAS bf16x8*)(lds + PG8_SB(b, h) + boff + n * 2048 + k * 1024); } while (0)
; #define PG8_MMA(ai, bj, At, Bt) do { __builtin_amdgcn_s_setprio(1); _Pragma("unroll") for (int m = 0; m < 4; ++m) _Pragma("unroll") for (int n = 0; n < 2; ++n) _Pragma("unroll") for (int k = 0; k < 2; ++k) \
;         acc[ai][bj][m][n] = __builtin_amdgcn_mfma_f32_16x16x32_bf16(Bt[n][k], At[m][k], acc[ai][bj][m][n], 0, 0, 0); __builtin_amdgcn_s_setprio(0); } while (0)
; #define PG8_WAIT_V(n) asm volatile("s_waitcnt vmcnt(" #n ")" ::: "memory")
; #define PG8_WAIT_L(n) asm volatile("s_waitcnt lgkmcnt(" #n ")" ::: "memory")
; #define PG8_BAR __builtin_amdgcn_s_barrier()
; #define PG8_SCHED __builtin_amdgcn_sched_barrier(0)
; template <class Epi, class Sched, bool ALIGN_EPI = false, bool SP2 = false>
; __device__ __forceinline__ void gemm_phase(PG8_LAS unsigned char* lds, const Gemm g, const Sched& S, const Epi& E) {
;     ...
;             PG8_LDA(At, 0, 1); PG8_STAGE(PG8_SB(0, 0), b2, voffB); PG8_STAGE(PG8_SB(0, 1), b2 + hstepB, voffB); PG8_STAGE(PG8_SA(0, 0), a2, voffA);
;             PG8_WAIT_V(8); PG8_WAIT_L(0); PG8_BAR; PG8_MMA(1, 0, At, B0); PG8_MMA(1, 1, At, B1); PG8_BAR; PG8_SCHED;
;             PG8_LDB(B0, 1, 0); PG8_LDB(B1, 1, 1); PG8_SCHED; PG8_LDA(At, 1, 0); PG8_STAGE(PG8_SA(0, 1), a2 + hstepA, voffA);
;             PG8_WAIT_V(8); PG8_WAIT_L(0); PG8_BAR; PG8_MMA(0, 0, At, B0); PG8_MMA(0, 1, At, B1); PG8_BAR; PG8_SCHED;
;             PG8_LDA(At, 1, 1); PG8_STAGE(PG8_SB(1, 0), b3, voffB); PG8_STAGE(PG8_SB(1, 1), b3 + hstepB, voffB); PG8_STAGE(PG8_SA(1, 0), a3, voffA);
	s_setprio 0
	s_add_i32 s66, s48, s4
	v_lshl_add_u64 v[222:223], s[36:37], 0, v[132:133]
	s_mov_b32 m0, s66
	ds_read_b128 v[190:193], v156 offset:16384
	ds_read_b128 v[194:197], v156 offset:17408
	ds_read_b128 v[198:201], v156 offset:18432
	ds_read_b128 v[202:205], v156 offset:19456
	ds_read_b128 v[206:209], v156 offset:20480
	ds_read_b128 v[210:213], v156 offset:21504
	ds_read_b128 v[214:217], v156 offset:22528
	ds_read_b128 v[218:221], v156 offset:23552
	global_load_lds_dwordx4 v[222:223], off
	s_add_i32 m0, s66, 0x2000
	s_add_u32 s66, s36, 0x40000
	v_lshl_add_u64 v[224:225], s[36:37], 0, v[136:137]
	s_addc_u32 s67, s37, 0
	s_add_i32 s68, s49, s4
	global_load_lds_dwordx4 v[224:225], off
	v_lshl_add_u64 v[226:227], s[66:67], 0, v[132:133]
	s_mov_b32 m0, s68
	v_lshl_add_u64 v[228:229], s[38:39], 0, v[134:135]
	global_load_lds_dwordx4 v[226:227], off
	v_lshl_add_u64 v[226:227], s[66:67], 0, v[136:137]
	s_add_i32 m0, s68, 0x2000
	s_nop 0
	global_load_lds_dwordx4 v[226:227], off
	v_lshl_add_u64 v[226:227], s[38:39], 0, v[130:131]
	s_mov_b32 m0, s33
	s_nop 0
	global_load_lds_dwordx4 v[226:227], off
	s_mov_b32 m0, s35
	s_nop 0
	global_load_lds_dwordx4 v[228:229], off
	s_waitcnt vmcnt(24)
	s_waitcnt lgkmcnt(0)
	s_setprio 1
	s_barrier
	v_mfma_f32_16x16x32_bf16 v[62:65], v[158:161], v[190:193], v[62:65]
	v_mfma_f32_16x16x32_bf16 v[58:61], v[166:169], v[190:193], v[58:61]
	v_mfma_f32_16x16x32_bf16 v[46:49], v[158:161], v[198:201], v[46:49]
	v_mfma_f32_16x16x32_bf16 v[42:45], v[166:169], v[198:201], v[42:45]
	v_mfma_f32_16x16x32_bf16 v[30:33], v[158:161], v[206:209], v[30:33]
	v_mfma_f32_16x16x32_bf16 v[26:29], v[166:169], v[206:209], v[26:29]
	v_mfma_f32_16x16x32_bf16 v[14:17], v[158:161], v[214:217], v[14:17]
	v_mfma_f32_16x16x32_bf16 v[10:13], v[166:169], v[214:217], v[10:13]
	v_mfma_f32_16x16x32_bf16 v[62:65], v[162:165], v[194:197], v[62:65]
	v_mfma_f32_16x16x32_bf16 v[58:61], v[170:173], v[194:197], v[58:61]
	v_mfma_f32_16x16x32_bf16 v[46:49], v[162:165], v[202:205], v[46:49]
	v_mfma_f32_16x16x32_bf16 v[42:45], v[170:173], v[202:205], v[42:45]
	v_mfma_f32_16x16x32_bf16 v[30:33], v[162:165], v[210:213], v[30:33]
	v_mfma_f32_16x16x32_bf16 v[26:29], v[170:173], v[210:213], v[26:29]
	v_mfma_f32_16x16x32_bf16 v[14:17], v[162:165], v[218:221], v[14:17]
	v_mfma_f32_16x16x32_bf16 v[10:13], v[170:173], v[218:221], v[10:13]
	v_mfma_f32_16x16x32_bf16 v[54:57], v[174:177], v[190:193], v[54:57]
	v_mfma_f32_16x16x32_bf16 v[50:53], v[182:185], v[190:193], v[50:53]
	v_mfma_f32_16x16x32_bf16 v[38:41], v[174:177], v[198:201], v[38:41]
	v_mfma_f32_16x16x32_bf16 v[34:37], v[182:185], v[198:201], v[34:37]
	v_mfma_f32_16x16x32_bf16 v[22:25], v[174:177], v[206:209], v[22:25]
	v_mfma_f32_16x16x32_bf16 v[18:21], v[182:185], v[206:209], v[18:21]
	v_mfma_f32_16x16x32_bf16 v[6:9], v[174:177], v[214:217], v[6:9]
	v_mfma_f32_16x16x32_bf16 v[2:5], v[182:185], v[214:217], v[2:5]
	v_mfma_f32_16x16x32_bf16 v[54:57], v[178:181], v[194:197], v[54:57]
	v_mfma_f32_16x16x32_bf16 v[50:53], v[186:189], v[194:197], v[50:53]
	v_mfma_f32_16x16x32_bf16 v[38:41], v[178:181], v[202:205], v[38:41]
	v_mfma_f32_16x16x32_bf16 v[34:37], v[186:189], v[202:205], v[34:37]
	v_mfma_f32_16x16x32_bf16 v[22:25], v[178:181], v[210:213], v[22:25]
	v_mfma_f32_16x16x32_bf16 v[18:21], v[186:189], v[210:213], v[18:21]
	v_mfma_f32_16x16x32_bf16 v[6:9], v[178:181], v[218:221], v[6:9]
	v_mfma_f32_16x16x32_bf16 v[2:5], v[186:189], v[218:221], v[2:5]
	s_barrier
	s_setprio 0
	s_add_i32 s66, 0, 0x18000
	v_add_u32_e32 v157, s66, v1
	s_add_i32 s67, 0, 0x1c000
	ds_read_b128 v[158:161], v157
	ds_read_b128 v[162:165], v157 offset:1024
	ds_read_b128 v[166:169], v157 offset:2048
	ds_read_b128 v[170:173], v157 offset:3072
	v_add_u32_e32 v157, s67, v1
	ds_read_b128 v[174:177], v157
	ds_read_b128 v[178:181], v157 offset:1024
	ds_read_b128 v[182:185], v157 offset:2048
	ds_read_b128 v[186:189], v157 offset:3072
	s_add_u32 s38, s38, 0x40000
	s_addc_u32 s39, s39, 0
	s_mov_b32 m0, s40
	v_lshl_add_u64 v[230:231], s[38:39], 0, v[130:131]
	ds_read_b128 v[190:193], v156 offset:32768
	ds_read_b128 v[194:197], v156 offset:33792
	ds_read_b128 v[198:201], v156 offset:34816
	ds_read_b128 v[202:205], v156 offset:35840
	ds_read_b128 v[206:209], v156 offset:36864
	ds_read_b128 v[210:213], v156 offset:37888
	ds_read_b128 v[214:217], v156 offset:38912
	ds_read_b128 v[218:221], v156 offset:39936
	global_load_lds_dwordx4 v[230:231], off
	v_lshl_add_u64 v[230:231], s[38:39], 0, v[134:135]
	s_mov_b32 m0, s41
	s_nop 0
	global_load_lds_dwordx4 v[230:231], off
	s_waitcnt vmcnt(24)
	s_waitcnt lgkmcnt(0)
	s_setprio 1
	s_barrier
; #define PG8_STAGE(bufoff, gbase, voff) do { _Pragma("unroll") for (int _i = 0; _i < 2; ++_i) \
;         __builtin_amdgcn_global_load_lds((const unsigned*)((const char*)(gbase) + (voff)[_i]), (PG8_LAS unsigned*)(lds + (bufoff) + ldsw + _i * 8192), 16, 0, 0); } while (0)
; #define PG8_LDA(dst, b, h) do { _Pragma("unroll") for (int m = 0; m < 4; ++m) _Pragma("unroll") for (int k = 0; k < 2; ++k) dst[m][k] = *(const PG8_LAS bf16x8*)(lds + PG8_SA(b, h) + aoff + m * 2048 + k * 1024); } while (0)
; #define PG8_MMA(ai, bj, At, Bt) do { __builtin_amdgcn_s_setprio(1); _Pragma("unroll") for (int m = 0; m < 4; ++m) _Pragma("unroll") for (int n = 0; n < 2; ++n) _Pragma("unroll") for (int k = 0; k < 2; ++k) \
;         acc[ai][bj][m][n] = __builtin_amdgcn_mfma_f32_16x16x32_bf16(Bt[n][k], At[m][k], acc[ai][bj][m][n], 0, 0, 0); __builtin_amdgcn_s_setprio(0); } while (0)
; #define PG8_WAIT_V(n) asm volatile("s_waitcnt vmcnt(" #n ")" ::: "memory")
; #define PG8_WAIT_L(n) asm volatile("s_waitcnt lgkmcnt(" #n ")" ::: "memory")
; #define PG8_BAR __builtin_amdgcn_s_barrier()
; #define PG8_SCHED __builtin_amdgcn_sched_barrier(0)
; template <class Epi, class Sched, bool ALIGN_EPI = false, bool SP2 = false>
; __device__ __forceinline__ void gemm_phase(PG8_LAS unsigned char* lds, const Gemm g, const Sched& S, const Epi& E) {
;     ...
;             PG8_WAIT_V(8); PG8_WAIT_L(0); PG8_BAR; PG8_MMA(0, 0, At, B0); PG8_MMA(0, 1, At, B1); PG8_BAR; PG8_SCHED;
;             PG8_LDA(At, 1, 1); PG8_STAGE(PG8_SB(1, 0), b3, voffB); PG8_STAGE(PG8_SB(1, 1), b3 + hstepB, voffB); PG8_STAGE(PG8_SA(1, 0), a3, voffA);
;             PG8_WAIT_V(8); PG8_WAIT_L(0); PG8_BAR; PG8_MMA(1, 0, At, B0); PG8_MMA(1, 1, At, B1); PG8_BAR; PG8_SCHED;
	v_mfma_f32_16x16x32_bf16 v[126:129], v[158:161], v[190:193], v[126:129]
	v_mfma_f32_16x16x32_bf16 v[122:125], v[166:169], v[190:193], v[122:125]
	v_mfma_f32_16x16x32_bf16 v[110:113], v[158:161], v[198:201], v[110:113]
	v_mfma_f32_16x16x32_bf16 v[106:109], v[166:169], v[198:201], v[106:109]
	v_mfma_f32_16x16x32_bf16 v[94:97], v[158:161], v[206:209], v[94:97]
	v_mfma_f32_16x16x32_bf16 v[90:93], v[166:169], v[206:209], v[90:93]
	v_mfma_f32_16x16x32_bf16 v[78:81], v[158:161], v[214:217], v[78:81]
	v_mfma_f32_16x16x32_bf16 v[74:77], v[166:169], v[214:217], v[74:77]
	v_mfma_f32_16x16x32_bf16 v[126:129], v[162:165], v[194:197], v[126:129]
	v_mfma_f32_16x16x32_bf16 v[122:125], v[170:173], v[194:197], v[122:125]
	v_mfma_f32_16x16x32_bf16 v[110:113], v[162:165], v[202:205], v[110:113]
	v_mfma_f32_16x16x32_bf16 v[106:109], v[170:173], v[202:205], v[106:109]
	v_mfma_f32_16x16x32_bf16 v[94:97], v[162:165], v[210:213], v[94:97]
	v_mfma_f32_16x16x32_bf16 v[90:93], v[170:173], v[210:213], v[90:93]
	v_mfma_f32_16x16x32_bf16 v[78:81], v[162:165], v[218:221], v[78:81]
	v_mfma_f32_16x16x32_bf16 v[74:77], v[170:173], v[218:221], v[74:77]
	v_mfma_f32_16x16x32_bf16 v[118:121], v[174:177], v[190:193], v[118:121]
	v_mfma_f32_16x16x32_bf16 v[114:117], v[182:185], v[190:193], v[114:117]
	v_mfma_f32_16x16x32_bf16 v[102:105], v[174:177], v[198:201], v[102:105]
	v_mfma_f32_16x16x32_bf16 v[98:101], v[182:185], v[198:201], v[98:101]
	v_mfma_f32_16x16x32_bf16 v[86:89], v[174:177], v[206:209], v[86:89]
	v_mfma_f32_16x16x32_bf16 v[82:85], v[182:185], v[206:209], v[82:85]
	v_mfma_f32_16x16x32_bf16 v[70:73], v[174:177], v[214:217], v[70:73]
	v_mfma_f32_16x16x32_bf16 v[66:69], v[182:185], v[214:217], v[66:69]
	v_mfma_f32_16x16x32_bf16 v[118:121], v[178:181], v[194:197], v[118:121]
	v_mfma_f32_16x16x32_bf16 v[114:117], v[186:189], v[194:197], v[114:117]
	v_mfma_f32_16x16x32_bf16 v[102:105], v[178:181], v[202:205], v[102:105]
	v_mfma_f32_16x16x32_bf16 v[98:101], v[186:189], v[202:205], v[98:101]
	v_mfma_f32_16x16x32_bf16 v[86:89], v[178:181], v[210:213], v[86:89]
	v_mfma_f32_16x16x32_bf16 v[82:85], v[186:189], v[210:213], v[82:85]
	v_mfma_f32_16x16x32_bf16 v[70:73], v[178:181], v[218:221], v[70:73]
	v_mfma_f32_16x16x32_bf16 v[66:69], v[186:189], v[218:221], v[66:69]
	s_barrier
	s_setprio 0
	s_add_i32 s38, s66, s4
	v_lshl_add_u64 v[222:223], v[222:223], 0, s[8:9]
	s_mov_b32 m0, s38
	ds_read_b128 v[190:193], v156 offset:49152
	ds_read_b128 v[194:197], v156 offset:50176
	ds_read_b128 v[198:201], v156 offset:51200
	ds_read_b128 v[202:205], v156 offset:52224
	ds_read_b128 v[206:209], v156 offset:53248
	ds_read_b128 v[210:213], v156 offset:54272
	ds_read_b128 v[214:217], v156 offset:55296
	ds_read_b128 v[218:221], v156 offset:56320
	global_load_lds_dwordx4 v[222:223], off
	s_add_i32 m0, s38, 0x2000
	s_add_u32 s36, s36, 0x40080
	v_lshl_add_u64 v[222:223], v[224:225], 0, s[8:9]
	s_addc_u32 s37, s37, 0
	s_add_i32 s38, s67, s4
	global_load_lds_dwordx4 v[222:223], off
	v_lshl_add_u64 v[222:223], s[36:37], 0, v[132:133]
	s_mov_b32 m0, s38
	s_nop 0
	global_load_lds_dwordx4 v[222:223], off
	v_lshl_add_u64 v[222:223], s[36:37], 0, v[136:137]
	s_add_i32 m0, s38, 0x2000
	s_nop 0
	global_load_lds_dwordx4 v[222:223], off
	v_lshl_add_u64 v[222:223], v[226:227], 0, s[8:9]
	s_mov_b32 m0, s45
	s_nop 0
	global_load_lds_dwordx4 v[222:223], off
	v_lshl_add_u64 v[222:223], v[228:229], 0, s[8:9]
	s_mov_b32 m0, s46
	s_nop 0
	global_load_lds_dwordx4 v[222:223], off
	s_waitcnt vmcnt(8)
	s_waitcnt lgkmcnt(0)
	s_setprio 1
	s_barrier
	v_mfma_f32_16x16x32_bf16 v[62:65], v[158:161], v[190:193], v[62:65]
	v_mfma_f32_16x16x32_bf16 v[58:61], v[166:169], v[190:193], v[58:61]
	v_mfma_f32_16x16x32_bf16 v[46:49], v[158:161], v[198:201], v[46:49]
	v_mfma_f32_16x16x32_bf16 v[42:45], v[166:169], v[198:201], v[42:45]
	v_mfma_f32_16x16x32_bf16 v[30:33], v[158:161], v[206:209], v[30:33]
	v_mfma_f32_16x16x32_bf16 v[26:29], v[166:169], v[206:209], v[26:29]
	v_mfma_f32_16x16x32_bf16 v[14:17], v[158:161], v[214:217], v[14:17]
	v_mfma_f32_16x16x32_bf16 v[10:13], v[166:169], v[214:217], v[10:13]
	v_mfma_f32_16x16x32_bf16 v[62:65], v[162:165], v[194:197], v[62:65]
	v_mfma_f32_16x16x32_bf16 v[58:61], v[170:173], v[194:197], v[58:61]
	v_mfma_f32_16x16x32_bf16 v[46:49], v[162:165], v[202:205], v[46:49]
	v_mfma_f32_16x16x32_bf16 v[42:45], v[170:173], v[202:205], v[42:45]
	v_mfma_f32_16x16x32_bf16 v[30:33], v[162:165], v[210:213], v[30:33]
	v_mfma_f32_16x16x32_bf16 v[26:29], v[170:173], v[210:213], v[26:29]
	v_mfma_f32_16x16x32_bf16 v[14:17], v[162:165], v[218:221], v[14:17]
	v_mfma_f32_16x16x32_bf16 v[10:13], v[170:173], v[218:221], v[10:13]
	v_mfma_f32_16x16x32_bf16 v[54:57], v[174:177], v[190:193], v[54:57]
	v_mfma_f32_16x16x32_bf16 v[50:53], v[182:185], v[190:193], v[50:53]
	v_mfma_f32_16x16x32_bf16 v[38:41], v[174:177], v[198:201], v[38:41]
	v_mfma_f32_16x16x32_bf16 v[34:37], v[182:185], v[198:201], v[34:37]
	v_mfma_f32_16x16x32_bf16 v[22:25], v[174:177], v[206:209], v[22:25]
	v_mfma_f32_16x16x32_bf16 v[18:21], v[182:185], v[206:209], v[18:21]
	v_mfma_f32_16x16x32_bf16 v[6:9], v[174:177], v[214:217], v[6:9]
	v_mfma_f32_16x16x32_bf16 v[2:5], v[182:185], v[214:217], v[2:5]
	v_mfma_f32_16x16x32_bf16 v[54:57], v[178:181], v[194:197], v[54:57]
	v_mfma_f32_16x16x32_bf16 v[50:53], v[186:189], v[194:197], v[50:53]
	v_mfma_f32_16x16x32_bf16 v[38:41], v[178:181], v[202:205], v[38:41]
	v_mfma_f32_16x16x32_bf16 v[34:37], v[186:189], v[202:205], v[34:37]
	v_mfma_f32_16x16x32_bf16 v[22:25], v[178:181], v[210:213], v[22:25]
	v_mfma_f32_16x16x32_bf16 v[18:21], v[186:189], v[210:213], v[18:21]
	v_mfma_f32_16x16x32_bf16 v[6:9], v[178:181], v[218:221], v[6:9]
	v_mfma_f32_16x16x32_bf16 v[2:5], v[186:189], v[218:221], v[2:5]
	s_barrier
	s_setprio 0
	s_add_i32 s65, s65, 2
	s_add_u32 s30, s30, 0x100
	s_addc_u32 s31, s31, 0
	s_add_u32 s63, s63, 0x100
	s_addc_u32 s64, s64, 0
	s_cmp_gt_u32 s65, 13
	s_cbranch_scc0 .LBB0_1244
; __device__ __forceinline__ u32x4 pack8(const f32x4 a, const f32x4 b) { u32x4 w; w.x = cvt_pk_bf16(a[0], a[1]); w.y = cvt_pk_bf16(a[2], a[3]); w.z = cvt_pk_bf16(b[0], b[1]); w.w = cvt_pk_bf16(b[2], b[3]); return w; }
; #define PG8_BAR __builtin_amdgcn_s_barrier()
;     __device__ __forceinline__ void operator()(const f32x4 (&acc)[2][2][4][2], const Unit& u, int wr, int wc, int fr, int fq) const {
;         const int rl0 = wr * 64 + fr, cin = 32 * (wc & 1) + 8 * fq;
; #pragma unroll
;         for (int ai = 0; ai < 2; ++ai)
; #pragma unroll
;             for (int m = 0; m < 4; ++m) {
; #pragma unroll
;                 for (int bj = 0; bj < 2; ++bj) { f32x4 v0 = acc[ai][bj][m][0], v1 = acc[ai][bj][m][1];
; #pragma unroll
;                     for (int i = 0; i < 4; ++i) { const float a = fmaxf(v0[i], 0.f), b = fmaxf(v1[i], 0.f); v0[i] = a * a; v1[i] = b * b; }
;                     *(u32x4*)(hb + ((size_t)(u.pm * 64 + u.pn * 4 + bj * 2 + (wc >> 1)) * 256 + rl0 + ai * HALF + m * 16) * 64 + cin) = pack8(v0, v1); } }
; template <class Epi, class Sched, bool ALIGN_EPI = false, bool SP2 = false>
; __device__ __forceinline__ void gemm_phase(PG8_LAS unsigned char* lds, const Gemm g, const Sched& S, const Epi& E) {
;     ...
;         if constexpr (ALIGN_EPI) { if (wr == 0) PG8_BAR; }
;         bool keep_ = false;
;         if constexpr (!Epi::AFTER_DRAIN) { if constexpr (Epi::CARRY) keep_ = E.carry(acc, cur, wr, wc, fr, fq); else E(acc, cur, wr, wc, fr, fq); S.done(cur); }
.Lub_p7_after:
	s_and_b64 vcc, exec, s[10:11]
	s_cbranch_vccz .LBB0_1247
	s_barrier
.LBB0_1247:
	s_mov_b32 s98, 1
	s_add_u32 s100, s51, 0x40080
	s_addc_u32 s101, s19, 0
	v_lshl_add_u64 v[222:223], s[100:101], 0, v[146:147]
	s_add_i32 m0, s33, 0xc000
	s_nop 0
	global_load_lds_dwordx4 v[222:223], off
	v_lshl_add_u64 v[222:223], s[100:101], 0, v[148:149]
	s_add_i32 m0, s33, 0xe000
	s_nop 0
	global_load_lds_dwordx4 v[222:223], off
	s_lshl_b32 s17, s28, 6
	s_lshl_b32 s19, s29, 2
	s_add_i32 s17, s17, s19
	s_or_b32 s30, s17, s47
	s_ashr_i32 s31, s30, 31
	s_lshl_b64 s[28:29], s[30:31], 15
	s_add_u32 s28, s26, s28
	v_max_f32_e32 v126, v126, v126
	v_max_f32_e32 v122, v122, v122
	v_max_f32_e32 v127, v127, v127
	v_max_f32_e32 v123, v123, v123
	s_addc_u32 s29, s27, s29
	s_or_b32 s30, s30, 2
	v_max_f32_e32 v126, 0, v126
	v_max_f32_e32 v122, 0, v122
	v_max_f32_e32 v127, 0, v127
	v_max_f32_e32 v123, 0, v123
	v_max_f32_e32 v128, v128, v128
	v_max_f32_e32 v124, v124, v124
	v_max_f32_e32 v129, v129, v129
	v_max_f32_e32 v125, v125, v125
	s_ashr_i32 s31, s30, 31
	v_pk_mul_f32 v[126:127], v[126:127], v[126:127]
	v_pk_mul_f32 v[122:123], v[122:123], v[122:123]
	v_max_f32_e32 v128, 0, v128
	v_max_f32_e32 v124, 0, v124
	v_max_f32_e32 v129, 0, v129
	v_max_f32_e32 v125, 0, v125
	v_max_f32_e32 v118, v118, v118
	v_max_f32_e32 v114, v114, v114
	v_max_f32_e32 v119, v119, v119
	v_max_f32_e32 v115, v115, v115
	s_lshl_b64 s[30:31], s[30:31], 15
	v_pk_mul_f32 v[128:129], v[128:129], v[128:129]
	v_pk_mul_f32 v[158:159], v[124:125], v[124:125]
	v_cvt_pk_bf16_f32 v124, v126, v127
	v_cvt_pk_bf16_f32 v126, v122, v123
	v_lshl_add_u64 v[122:123], s[28:29], 0, v[140:141]
	v_max_f32_e32 v118, 0, v118
	v_max_f32_e32 v114, 0, v114
	v_max_f32_e32 v119, 0, v119
	v_max_f32_e32 v115, 0, v115
	v_max_f32_e32 v120, v120, v120
	v_max_f32_e32 v116, v116, v116
	v_max_f32_e32 v121, v121, v121
	v_max_f32_e32 v117, v117, v117
	s_add_u32 s30, s26, s30
	v_cvt_pk_bf16_f32 v125, v128, v129
	v_cvt_pk_bf16_f32 v127, v158, v159
	v_lshl_add_u64 v[122:123], v[122:123], 0, v[138:139]
	v_pk_mul_f32 v[118:119], v[118:119], v[118:119]
	v_pk_mul_f32 v[114:115], v[114:115], v[114:115]
	v_max_f32_e32 v120, 0, v120
	v_max_f32_e32 v116, 0, v116
	v_max_f32_e32 v121, 0, v121
	v_max_f32_e32 v117, 0, v117
	s_addc_u32 s31, s27, s31
	global_store_dwordx4 v[122:123], v[124:127], off
	v_pk_mul_f32 v[120:121], v[120:121], v[120:121]
	v_max_f32_e32 v106, v106, v106
	v_pk_mul_f32 v[124:125], v[116:117], v[116:117]
	v_cvt_pk_bf16_f32 v116, v118, v119
	v_cvt_pk_bf16_f32 v118, v114, v115
	v_lshl_add_u64 v[114:115], s[30:31], 0, v[140:141]
	v_max_f32_e32 v107, v107, v107
	v_cvt_pk_bf16_f32 v117, v120, v121
	v_cvt_pk_bf16_f32 v119, v124, v125
	v_lshl_add_u64 v[114:115], v[114:115], 0, v[138:139]
	v_max_f32_e32 v106, 0, v106
	v_max_f32_e32 v107, 0, v107
	global_store_dwordx4 v[114:115], v[116:119], off
	v_max_f32_e32 v110, v110, v110
	v_max_f32_e32 v111, v111, v111
	v_pk_mul_f32 v[116:117], v[106:107], v[106:107]
	v_max_f32_e32 v107, v108, v108
	v_max_f32_e32 v106, v112, v112
	v_max_f32_e32 v108, 0, v107
	v_max_f32_e32 v107, v113, v113
	v_max_f32_e32 v109, v109, v109
	v_max_f32_e32 v110, 0, v110
	v_max_f32_e32 v111, 0, v111
	v_max_f32_e32 v106, 0, v106
	v_max_f32_e32 v107, 0, v107
	v_max_f32_e32 v109, 0, v109
	v_pk_mul_f32 v[110:111], v[110:111], v[110:111]
	v_pk_mul_f32 v[112:113], v[106:107], v[106:107]
	v_pk_mul_f32 v[118:119], v[108:109], v[108:109]
	v_max_f32_e32 v98, v98, v98
	v_max_f32_e32 v99, v99, v99
	v_cvt_pk_bf16_f32 v106, v110, v111
	v_cvt_pk_bf16_f32 v107, v112, v113
	v_cvt_pk_bf16_f32 v108, v116, v117
	v_cvt_pk_bf16_f32 v109, v118, v119
	v_max_f32_e32 v98, 0, v98
	v_max_f32_e32 v99, 0, v99
	global_store_dwordx4 v[122:123], v[106:109], off offset:2048
	v_max_f32_e32 v102, v102, v102
	v_max_f32_e32 v103, v103, v103
	v_pk_mul_f32 v[106:107], v[98:99], v[98:99]
	v_max_f32_e32 v99, v100, v100
	v_max_f32_e32 v98, v104, v104
	v_max_f32_e32 v100, 0, v99
	v_max_f32_e32 v99, v105, v105
	v_max_f32_e32 v101, v101, v101
	v_max_f32_e32 v102, 0, v102
	v_max_f32_e32 v103, 0, v103
	v_max_f32_e32 v98, 0, v98
	v_max_f32_e32 v99, 0, v99
	v_max_f32_e32 v101, 0, v101
	v_pk_mul_f32 v[102:103], v[102:103], v[102:103]
	v_pk_mul_f32 v[104:105], v[98:99], v[98:99]
	v_pk_mul_f32 v[108:109], v[100:101], v[100:101]
	v_max_f32_e32 v90, v90, v90
	v_max_f32_e32 v91, v91, v91
	v_cvt_pk_bf16_f32 v98, v102, v103
	v_cvt_pk_bf16_f32 v99, v104, v105
	v_cvt_pk_bf16_f32 v100, v106, v107
	v_cvt_pk_bf16_f32 v101, v108, v109
	v_max_f32_e32 v90, 0, v90
	v_max_f32_e32 v91, 0, v91
	global_store_dwordx4 v[114:115], v[98:101], off offset:2048
	v_max_f32_e32 v94, v94, v94
	v_max_f32_e32 v95, v95, v95
	v_pk_mul_f32 v[98:99], v[90:91], v[90:91]
	v_max_f32_e32 v91, v92, v92
	v_max_f32_e32 v94, 0, v94
	v_max_f32_e32 v95, 0, v95
	v_max_f32_e32 v90, v96, v96
	v_max_f32_e32 v92, 0, v91
	v_max_f32_e32 v91, v97, v97
	v_max_f32_e32 v93, v93, v93
	v_pk_mul_f32 v[94:95], v[94:95], v[94:95]
	v_max_f32_e32 v90, 0, v90
	v_max_f32_e32 v91, 0, v91
	v_max_f32_e32 v93, 0, v93
	v_pk_mul_f32 v[96:97], v[90:91], v[90:91]
	v_pk_mul_f32 v[100:101], v[92:93], v[92:93]
	v_cvt_pk_bf16_f32 v90, v94, v95
	v_lshl_add_u64 v[94:95], s[28:29], 0, v[142:143]
	v_max_f32_e32 v82, v82, v82
	v_max_f32_e32 v83, v83, v83
	v_cvt_pk_bf16_f32 v91, v96, v97
	v_cvt_pk_bf16_f32 v92, v98, v99
	v_cvt_pk_bf16_f32 v93, v100, v101
	v_lshl_add_u64 v[94:95], v[94:95], 0, v[138:139]
	v_max_f32_e32 v82, 0, v82
	v_max_f32_e32 v83, 0, v83
	global_store_dwordx4 v[94:95], v[90:93], off
	v_max_f32_e32 v86, v86, v86
	v_max_f32_e32 v87, v87, v87
	v_pk_mul_f32 v[90:91], v[82:83], v[82:83]
	v_max_f32_e32 v83, v84, v84
; __device__ __forceinline__ u32x4 pack8(const f32x4 a, const f32x4 b) { u32x4 w; w.x = cvt_pk_bf16(a[0], a[1]); w.y = cvt_pk_bf16(a[2], a[3]); w.z = cvt_pk_bf16(b[0], b[1]); w.w = cvt_pk_bf16(b[2], b[3]); return w; }
;     __device__ __forceinline__ void operator()(const f32x4 (&acc)[2][2][4][2], const Unit& u, int wr, int wc, int fr, int fq) const {
;     ...
;             for (int m = 0; m < 4; ++m) {
; #pragma unroll
;                 for (int bj = 0; bj < 2; ++bj) { f32x4 v0 = acc[ai][bj][m][0], v1 = acc[ai][bj][m][1];
; #pragma unroll
;                     for (int i = 0; i < 4; ++i) { const float a = fmaxf(v0[i], 0.f), b = fmaxf(v1[i], 0.f); v0[i] = a * a; v1[i] = b * b; }
;                     *(u32x4*)(hb + ((size_t)(u.pm * 64 + u.pn * 4 + bj * 2 + (wc >> 1)) * 256 + rl0 + ai * HALF + m * 16) * 64 + cin) = pack8(v0, v1); } }
	v_max_f32_e32 v86, 0, v86
	v_max_f32_e32 v87, 0, v87
	v_max_f32_e32 v82, v88, v88
	v_max_f32_e32 v84, 0, v83
	v_max_f32_e32 v83, v89, v89
	v_max_f32_e32 v85, v85, v85
	v_pk_mul_f32 v[86:87], v[86:87], v[86:87]
	v_max_f32_e32 v82, 0, v82
	v_max_f32_e32 v83, 0, v83
	v_max_f32_e32 v85, 0, v85
	v_pk_mul_f32 v[88:89], v[82:83], v[82:83]
	v_pk_mul_f32 v[92:93], v[84:85], v[84:85]
	v_cvt_pk_bf16_f32 v82, v86, v87
	v_lshl_add_u64 v[86:87], s[30:31], 0, v[142:143]
	v_max_f32_e32 v74, v74, v74
	v_max_f32_e32 v75, v75, v75
	v_cvt_pk_bf16_f32 v83, v88, v89
	v_cvt_pk_bf16_f32 v84, v90, v91
	v_cvt_pk_bf16_f32 v85, v92, v93
	v_lshl_add_u64 v[86:87], v[86:87], 0, v[138:139]
	v_max_f32_e32 v74, 0, v74
	v_max_f32_e32 v75, 0, v75
	global_store_dwordx4 v[86:87], v[82:85], off
	v_max_f32_e32 v78, v78, v78
	v_max_f32_e32 v79, v79, v79
	v_pk_mul_f32 v[82:83], v[74:75], v[74:75]
	v_max_f32_e32 v75, v76, v76
	v_max_f32_e32 v78, 0, v78
	v_max_f32_e32 v79, 0, v79
	v_max_f32_e32 v74, v80, v80
	v_max_f32_e32 v76, 0, v75
	v_max_f32_e32 v75, v81, v81
	v_max_f32_e32 v77, v77, v77
	v_pk_mul_f32 v[78:79], v[78:79], v[78:79]
	v_max_f32_e32 v74, 0, v74
	v_max_f32_e32 v75, 0, v75
	v_max_f32_e32 v77, 0, v77
	v_pk_mul_f32 v[80:81], v[74:75], v[74:75]
	v_pk_mul_f32 v[84:85], v[76:77], v[76:77]
	v_cvt_pk_bf16_f32 v74, v78, v79
	v_lshl_add_u64 v[78:79], s[28:29], 0, v[144:145]
	v_max_f32_e32 v66, v66, v66
	v_max_f32_e32 v67, v67, v67
	v_cvt_pk_bf16_f32 v75, v80, v81
	v_cvt_pk_bf16_f32 v76, v82, v83
	v_cvt_pk_bf16_f32 v77, v84, v85
	v_lshl_add_u64 v[78:79], v[78:79], 0, v[138:139]
	v_max_f32_e32 v66, 0, v66
	v_max_f32_e32 v67, 0, v67
	global_store_dwordx4 v[78:79], v[74:77], off
	v_max_f32_e32 v70, v70, v70
	v_max_f32_e32 v71, v71, v71
	v_pk_mul_f32 v[74:75], v[66:67], v[66:67]
	v_max_f32_e32 v67, v68, v68
	v_max_f32_e32 v70, 0, v70
	v_max_f32_e32 v71, 0, v71
	v_max_f32_e32 v66, v72, v72
	v_max_f32_e32 v68, 0, v67
	v_max_f32_e32 v67, v73, v73
	v_max_f32_e32 v69, v69, v69
	v_pk_mul_f32 v[70:71], v[70:71], v[70:71]
	v_max_f32_e32 v66, 0, v66
	v_max_f32_e32 v67, 0, v67
	v_max_f32_e32 v69, 0, v69
	v_pk_mul_f32 v[72:73], v[66:67], v[66:67]
	v_pk_mul_f32 v[76:77], v[68:69], v[68:69]
	v_cvt_pk_bf16_f32 v66, v70, v71
	v_lshl_add_u64 v[70:71], s[30:31], 0, v[144:145]
	v_max_f32_e32 v58, v58, v58
	v_max_f32_e32 v59, v59, v59
	v_cvt_pk_bf16_f32 v67, v72, v73
	v_cvt_pk_bf16_f32 v68, v74, v75
	v_cvt_pk_bf16_f32 v69, v76, v77
	v_lshl_add_u64 v[70:71], v[70:71], 0, v[138:139]
	v_max_f32_e32 v58, 0, v58
	v_max_f32_e32 v59, 0, v59
	global_store_dwordx4 v[70:71], v[66:69], off
	v_max_f32_e32 v62, v62, v62
	v_max_f32_e32 v63, v63, v63
	v_pk_mul_f32 v[66:67], v[58:59], v[58:59]
	v_max_f32_e32 v59, v60, v60
	v_max_f32_e32 v62, 0, v62
	v_max_f32_e32 v63, 0, v63
	v_max_f32_e32 v58, v64, v64
	v_max_f32_e32 v60, 0, v59
	v_max_f32_e32 v59, v65, v65
	v_pk_mul_f32 v[62:63], v[62:63], v[62:63]
	v_max_f32_e32 v58, 0, v58
	v_max_f32_e32 v59, 0, v59
	v_max_f32_e32 v61, v61, v61
	v_pk_mul_f32 v[64:65], v[58:59], v[58:59]
	v_cvt_pk_bf16_f32 v58, v62, v63
	v_add_co_u32_e32 v62, vcc, s43, v122
	v_max_f32_e32 v61, 0, v61
	s_nop 0
	v_addc_co_u32_e32 v63, vcc, 0, v123, vcc
	v_pk_mul_f32 v[68:69], v[60:61], v[60:61]
	v_cvt_pk_bf16_f32 v59, v64, v65
	v_add_co_u32_e32 v64, vcc, s50, v122
	v_max_f32_e32 v50, v50, v50
	v_max_f32_e32 v51, v51, v51
	v_cvt_pk_bf16_f32 v60, v66, v67
	v_cvt_pk_bf16_f32 v61, v68, v69
	v_addc_co_u32_e32 v65, vcc, 0, v123, vcc
	v_max_f32_e32 v50, 0, v50
	v_max_f32_e32 v51, 0, v51
	global_store_dwordx4 v[64:65], v[58:61], off offset:-4096
	v_max_f32_e32 v54, v54, v54
	v_max_f32_e32 v55, v55, v55
	v_pk_mul_f32 v[58:59], v[50:51], v[50:51]
	v_max_f32_e32 v51, v52, v52
	v_max_f32_e32 v54, 0, v54
	v_max_f32_e32 v55, 0, v55
	v_max_f32_e32 v50, v56, v56
	v_max_f32_e32 v52, 0, v51
	v_max_f32_e32 v51, v57, v57
	v_pk_mul_f32 v[54:55], v[54:55], v[54:55]
	v_max_f32_e32 v50, 0, v50
	v_max_f32_e32 v51, 0, v51
	v_max_f32_e32 v53, v53, v53
	v_pk_mul_f32 v[56:57], v[50:51], v[50:51]
	v_cvt_pk_bf16_f32 v50, v54, v55
	v_add_co_u32_e32 v54, vcc, s43, v114
	v_max_f32_e32 v53, 0, v53
	s_nop 0
	v_addc_co_u32_e32 v55, vcc, 0, v115, vcc
	v_pk_mul_f32 v[60:61], v[52:53], v[52:53]
	v_cvt_pk_bf16_f32 v51, v56, v57
	v_add_co_u32_e32 v56, vcc, s50, v114
	v_max_f32_e32 v42, v42, v42
	v_max_f32_e32 v43, v43, v43
	v_cvt_pk_bf16_f32 v52, v58, v59
	v_cvt_pk_bf16_f32 v53, v60, v61
	v_addc_co_u32_e32 v57, vcc, 0, v115, vcc
	v_max_f32_e32 v42, 0, v42
	v_max_f32_e32 v43, 0, v43
	global_store_dwordx4 v[56:57], v[50:53], off offset:-4096
	v_max_f32_e32 v46, v46, v46
	v_max_f32_e32 v47, v47, v47
	v_pk_mul_f32 v[50:51], v[42:43], v[42:43]
	v_max_f32_e32 v43, v44, v44
	v_max_f32_e32 v42, v48, v48
; __device__ __forceinline__ u32x4 pack8(const f32x4 a, const f32x4 b) { u32x4 w; w.x = cvt_pk_bf16(a[0], a[1]); w.y = cvt_pk_bf16(a[2], a[3]); w.z = cvt_pk_bf16(b[0], b[1]); w.w = cvt_pk_bf16(b[2], b[3]); return w; }
; #define PG8_BAR __builtin_amdgcn_s_barrier()
;     __device__ __forceinline__ void operator()(const f32x4 (&acc)[2][2][4][2], const Unit& u, int wr, int wc, int fr, int fq) const {
;     ...
;             for (int m = 0; m < 4; ++m) {
; #pragma unroll
;                 for (int bj = 0; bj < 2; ++bj) { f32x4 v0 = acc[ai][bj][m][0], v1 = acc[ai][bj][m][1];
; #pragma unroll
;                     for (int i = 0; i < 4; ++i) { const float a = fmaxf(v0[i], 0.f), b = fmaxf(v1[i], 0.f); v0[i] = a * a; v1[i] = b * b; }
;                     *(u32x4*)(hb + ((size_t)(u.pm * 64 + u.pn * 4 + bj * 2 + (wc >> 1)) * 256 + rl0 + ai * HALF + m * 16) * 64 + cin) = pack8(v0, v1); } }
; template <class Epi, class Sched, bool ALIGN_EPI = false, bool SP2 = false>
; __device__ __forceinline__ void gemm_phase(PG8_LAS unsigned char* lds, const Gemm g, const Sched& S, const Epi& E) {
;     ...
;         bool keep_ = false;
;         if constexpr (!Epi::AFTER_DRAIN) { if constexpr (Epi::CARRY) keep_ = E.carry(acc, cur, wr, wc, fr, fq); else E(acc, cur, wr, wc, fr, fq); S.done(cur); }
;         if (!has_next) break;
;         if (!keep_) {
; #pragma unroll
;         for (int a = 0; a < 2; ++a)
; #pragma unroll
;             for (int b = 0; b < 2; ++b)
; #pragma unroll
;                 for (int m = 0; m < 4; ++m)
; #pragma unroll
;                     for (int n = 0; n < 2; ++n) acc[a][b][m][n] = (f32x4){0.f, 0.f, 0.f, 0.f};
;         }
;         cur = nxt; cA = nA; cB = nB; ++ui;
;         if constexpr (ALIGN_EPI) { if (wr == 1) PG8_BAR; }
;     }
	v_max_f32_e32 v44, 0, v43
	v_max_f32_e32 v43, v49, v49
	v_max_f32_e32 v45, v45, v45
	v_max_f32_e32 v46, 0, v46
	v_max_f32_e32 v47, 0, v47
	v_max_f32_e32 v42, 0, v42
	v_max_f32_e32 v43, 0, v43
	v_max_f32_e32 v45, 0, v45
	v_pk_mul_f32 v[46:47], v[46:47], v[46:47]
	v_pk_mul_f32 v[48:49], v[42:43], v[42:43]
	v_pk_mul_f32 v[52:53], v[44:45], v[44:45]
	v_max_f32_e32 v34, v34, v34
	v_max_f32_e32 v35, v35, v35
	v_cvt_pk_bf16_f32 v42, v46, v47
	v_cvt_pk_bf16_f32 v43, v48, v49
	v_cvt_pk_bf16_f32 v44, v50, v51
	v_cvt_pk_bf16_f32 v45, v52, v53
	v_max_f32_e32 v34, 0, v34
	v_max_f32_e32 v35, 0, v35
	global_store_dwordx4 v[62:63], v[42:45], off offset:2048
	v_max_f32_e32 v38, v38, v38
	v_max_f32_e32 v39, v39, v39
	v_pk_mul_f32 v[42:43], v[34:35], v[34:35]
	v_max_f32_e32 v35, v36, v36
	v_max_f32_e32 v34, v40, v40
	v_max_f32_e32 v36, 0, v35
	v_max_f32_e32 v35, v41, v41
	v_max_f32_e32 v37, v37, v37
	v_max_f32_e32 v38, 0, v38
	v_max_f32_e32 v39, 0, v39
	v_max_f32_e32 v34, 0, v34
	v_max_f32_e32 v35, 0, v35
	v_max_f32_e32 v37, 0, v37
	v_pk_mul_f32 v[38:39], v[38:39], v[38:39]
	v_pk_mul_f32 v[40:41], v[34:35], v[34:35]
	v_pk_mul_f32 v[44:45], v[36:37], v[36:37]
	v_max_f32_e32 v26, v26, v26
	v_max_f32_e32 v27, v27, v27
	v_cvt_pk_bf16_f32 v34, v38, v39
	v_cvt_pk_bf16_f32 v35, v40, v41
	v_cvt_pk_bf16_f32 v36, v42, v43
	v_cvt_pk_bf16_f32 v37, v44, v45
	v_max_f32_e32 v26, 0, v26
	v_max_f32_e32 v27, 0, v27
	global_store_dwordx4 v[54:55], v[34:37], off offset:2048
	v_max_f32_e32 v30, v30, v30
	v_max_f32_e32 v31, v31, v31
	v_pk_mul_f32 v[34:35], v[26:27], v[26:27]
	v_max_f32_e32 v27, v28, v28
	v_max_f32_e32 v26, v32, v32
	v_max_f32_e32 v28, 0, v27
	v_max_f32_e32 v27, v33, v33
	v_max_f32_e32 v29, v29, v29
	v_max_f32_e32 v30, 0, v30
	v_max_f32_e32 v31, 0, v31
	v_max_f32_e32 v26, 0, v26
	v_max_f32_e32 v27, 0, v27
	v_max_f32_e32 v29, 0, v29
	v_pk_mul_f32 v[30:31], v[30:31], v[30:31]
	v_pk_mul_f32 v[32:33], v[26:27], v[26:27]
	v_pk_mul_f32 v[36:37], v[28:29], v[28:29]
	v_max_f32_e32 v18, v18, v18
	v_max_f32_e32 v19, v19, v19
	v_cvt_pk_bf16_f32 v26, v30, v31
	v_cvt_pk_bf16_f32 v27, v32, v33
	v_cvt_pk_bf16_f32 v28, v34, v35
	v_cvt_pk_bf16_f32 v29, v36, v37
	v_max_f32_e32 v18, 0, v18
	v_max_f32_e32 v19, 0, v19
	global_store_dwordx4 v[64:65], v[26:29], off
	v_max_f32_e32 v22, v22, v22
	v_max_f32_e32 v23, v23, v23
	v_pk_mul_f32 v[26:27], v[18:19], v[18:19]
	v_max_f32_e32 v19, v20, v20
	v_max_f32_e32 v18, v24, v24
	v_max_f32_e32 v20, 0, v19
	v_max_f32_e32 v19, v25, v25
	v_max_f32_e32 v21, v21, v21
	v_max_f32_e32 v22, 0, v22
	v_max_f32_e32 v23, 0, v23
	v_max_f32_e32 v18, 0, v18
	v_max_f32_e32 v19, 0, v19
	v_max_f32_e32 v21, 0, v21
	v_pk_mul_f32 v[22:23], v[22:23], v[22:23]
	v_pk_mul_f32 v[24:25], v[18:19], v[18:19]
	v_pk_mul_f32 v[28:29], v[20:21], v[20:21]
	v_max_f32_e32 v10, v10, v10
	v_max_f32_e32 v11, v11, v11
	v_cvt_pk_bf16_f32 v18, v22, v23
	v_cvt_pk_bf16_f32 v19, v24, v25
	v_cvt_pk_bf16_f32 v20, v26, v27
	v_cvt_pk_bf16_f32 v21, v28, v29
	v_max_f32_e32 v10, 0, v10
	v_max_f32_e32 v11, 0, v11
	global_store_dwordx4 v[56:57], v[18:21], off
	v_max_f32_e32 v14, v14, v14
	v_max_f32_e32 v15, v15, v15
	v_pk_mul_f32 v[18:19], v[10:11], v[10:11]
	v_max_f32_e32 v11, v12, v12
	v_max_f32_e32 v10, v16, v16
	v_max_f32_e32 v12, 0, v11
	v_max_f32_e32 v11, v17, v17
	v_max_f32_e32 v13, v13, v13
	v_max_f32_e32 v14, 0, v14
	v_max_f32_e32 v15, 0, v15
	v_max_f32_e32 v10, 0, v10
	v_max_f32_e32 v11, 0, v11
	v_max_f32_e32 v13, 0, v13
	v_pk_mul_f32 v[14:15], v[14:15], v[14:15]
	v_pk_mul_f32 v[16:17], v[10:11], v[10:11]
	v_pk_mul_f32 v[20:21], v[12:13], v[12:13]
	v_max_f32_e32 v2, v2, v2
	v_max_f32_e32 v3, v3, v3
	v_cvt_pk_bf16_f32 v10, v14, v15
	v_cvt_pk_bf16_f32 v11, v16, v17
	v_cvt_pk_bf16_f32 v12, v18, v19
	v_cvt_pk_bf16_f32 v13, v20, v21
	v_max_f32_e32 v2, 0, v2
	v_max_f32_e32 v3, 0, v3
	global_store_dwordx4 v[64:65], v[10:13], off offset:2048
	v_max_f32_e32 v6, v6, v6
	v_max_f32_e32 v7, v7, v7
	v_pk_mul_f32 v[10:11], v[2:3], v[2:3]
	v_max_f32_e32 v3, v4, v4
	v_max_f32_e32 v2, v8, v8
	v_max_f32_e32 v4, 0, v3
	v_max_f32_e32 v3, v9, v9
	v_max_f32_e32 v5, v5, v5
	v_max_f32_e32 v6, 0, v6
	v_max_f32_e32 v7, 0, v7
	v_max_f32_e32 v2, 0, v2
	v_max_f32_e32 v3, 0, v3
	v_max_f32_e32 v5, 0, v5
	v_pk_mul_f32 v[6:7], v[6:7], v[6:7]
	v_pk_mul_f32 v[8:9], v[2:3], v[2:3]
	v_pk_mul_f32 v[12:13], v[4:5], v[4:5]
	v_cvt_pk_bf16_f32 v2, v6, v7
	v_cvt_pk_bf16_f32 v3, v8, v9
	v_cvt_pk_bf16_f32 v4, v10, v11
	v_cvt_pk_bf16_f32 v5, v12, v13
	s_andn2_b64 vcc, exec, s[0:1]
	s_mov_b64 s[0:1], -1
	global_store_dwordx4 v[56:57], v[2:5], off offset:2048
	s_cbranch_vccnz .LBB0_1236
	s_andn2_b64 vcc, exec, s[6:7]
	s_cbranch_vccnz .LBB0_1235
	s_barrier
	s_branch .LBB0_1235

; __global__ void __launch_bounds__(NWAVES * 64, 2) fwd(Args args) {
	.amdhsa_kernel _Z3fwd4Args
		.amdhsa_group_segment_fixed_size 0
		.amdhsa_private_segment_fixed_size 0
		.amdhsa_kernarg_size 424
		.amdhsa_user_sgpr_count 2
		.amdhsa_user_sgpr_dispatch_ptr 0
		.amdhsa_user_sgpr_queue_ptr 0
		.amdhsa_user_sgpr_kernarg_segment_ptr 1
		.amdhsa_user_sgpr_dispatch_id 0
		.amdhsa_user_sgpr_kernarg_preload_length 0
		.amdhsa_user_sgpr_kernarg_preload_offset 0
		.amdhsa_user_sgpr_private_segment_size 0
		.amdhsa_uses_dynamic_stack 0
		.amdhsa_enable_private_segment 0
		.amdhsa_system_sgpr_workgroup_id_x 1
		.amdhsa_system_sgpr_workgroup_id_y 0
		.amdhsa_system_sgpr_workgroup_id_z 0
		.amdhsa_system_sgpr_workgroup_info 0
		.amdhsa_system_vgpr_workitem_id 0
		.amdhsa_next_free_vgpr 248
		.amdhsa_next_free_sgpr 102
		.amdhsa_accum_offset 244
		.amdhsa_reserve_vcc 1
		.amdhsa_float_round_mode_32 0
		.amdhsa_float_round_mode_16_64 0
		.amdhsa_float_denorm_mode_32 3
		.amdhsa_float_denorm_mode_16_64 3
		.amdhsa_dx10_clamp 1
		.amdhsa_ieee_mode 1
		.amdhsa_fp16_overflow 0
		.amdhsa_tg_split 0
		.amdhsa_exception_fp_ieee_invalid_op 0
		.amdhsa_exception_fp_denorm_src 0
		.amdhsa_exception_fp_ieee_div_zero 0
		.amdhsa_exception_fp_ieee_overflow 0
		.amdhsa_exception_fp_ieee_underflow 0
		.amdhsa_exception_fp_ieee_inexact 0
		.amdhsa_exception_int_div_zero 0
	.end_amdhsa_kernel

; __global__ void __launch_bounds__(NWAVES * 64, 2) fwd(Args args) {
amdhsa.kernels:
  - .agpr_count:     0
    .args:
      - .offset:         0
        .size:           168
        .value_kind:     by_value
      - .offset:         168
        .size:           4
        .value_kind:     hidden_block_count_x
      - .offset:         172
        .size:           4
        .value_kind:     hidden_block_count_y
      - .offset:         176
        .size:           4
        .value_kind:     hidden_block_count_z
      - .offset:         180
        .size:           2
        .value_kind:     hidden_group_size_x
      - .offset:         182
        .size:           2
        .value_kind:     hidden_group_size_y
      - .offset:         184
        .size:           2
        .value_kind:     hidden_group_size_z
      - .offset:         186
        .size:           2
        .value_kind:     hidden_remainder_x
      - .offset:         188
        .size:           2
        .value_kind:     hidden_remainder_y
      - .offset:         190
        .size:           2
        .value_kind:     hidden_remainder_z
      - .offset:         208
        .size:           8
        .value_kind:     hidden_global_offset_x
      - .offset:         216
        .size:           8
        .value_kind:     hidden_global_offset_y
      - .offset:         224
        .size:           8
        .value_kind:     hidden_global_offset_z
      - .offset:         232
        .size:           2
        .value_kind:     hidden_grid_dims
      - .offset:         288
        .size:           4
        .value_kind:     hidden_dynamic_lds_size
    .group_segment_fixed_size: 0
    .kernarg_segment_align: 8
    .kernarg_segment_size: 424
    .language:       OpenCL C
    .language_version:
      - 2
      - 0
    .max_flat_workgroup_size: 512
    .name:           _Z3fwd4Args
    .private_segment_fixed_size: 0
    .sgpr_count:     108
    .sgpr_spill_count: 37
    .symbol:         _Z3fwd4Args.kd
    .uniform_work_group_size: 1
    .uses_dynamic_stack: false
    .vgpr_count:     248
    .vgpr_spill_count: 0
    .wavefront_size: 64
